# adds hand-restructured g2 main loops (P2 both instances, P9): LDS reads first, DMA interleaved with MFMA, persistent DMA addresses
# speedup vs baseline: 1.0322x; 1.0020x over previous
; DEVI int opaque_tid() { int t = (int)threadIdx.x; asm volatile("" : "+v"(t)); return t; }
; DEVI void g2_issue(const G2Tile& t, int kt, int st, char* smem) {
;     const int tid = opaque_tid(), lane = tid & 63, w = tid >> 6;
;     const int rr = lane >> 2, sch = (lane & 3) ^ ((lane >> 5) << 1);
;     const bf16_t* ap = t.A + (size_t)kt * 32 + (size_t)(w * 16 + rr) * t.lda + sch * 8;
;     const bf16_t* bp = t.Bt + (size_t)kt * 32 + (size_t)(w * 16 + rr) * t.ldb + sch * 8;
;     char* sa = smem + st * 24576 + w * 1024 + lane * 16;
; #pragma unroll
;     for (int i = 0; i < 4; ++i) __builtin_amdgcn_global_load_lds((const unsigned*)(ap + (size_t)(64 * i) * t.lda), (unsigned*)(sa + i * 4096), 16, 0, 0);
; #pragma unroll
;     for (int i = 0; i < 2; ++i) __builtin_amdgcn_global_load_lds((const unsigned*)(bp + (size_t)(64 * i) * t.ldb), (unsigned*)(sa + 16384 + i * 4096), 16, 0, 0);
; }
; DEVI void g2_prologue(const G2Tile& t, int st, char* smem) {
;     g2_issue(t, 0, st, smem);
;     g2_issue(t, 1, st == 2 ? 0 : st + 1, smem);
; }
; template <bool TRANS, class Epi>
; DEVI int g2_body(const G2Tile& t, int st, char* smem, bool has_next, const G2Tile& nxt, const Epi& epi) {
;     const int tid = opaque_tid(), lane = tid & 63, w = tid >> 6, wr = w >> 1, wc = w & 1, fr = lane & 15, fq = lane >> 4;
;     f32x4 acc[8][4];
; #pragma unroll
;     for (int m = 0; m < 8; ++m)
; #pragma unroll
;         for (int n = 0; n < 4; ++n) acc[m][n] = (f32x4){0.f, 0.f, 0.f, 0.f};
;     const int frag = fr * 64 + ((fq ^ ((fr >> 3) << 1)) << 4);
;     const int nk = t.nk;
.LBB0_241:
	s_cmp_eq_u32 s4, 0
	s_cbranch_scc1 .LBB0_279
	v_mov_b32_e32 v130, v172
	s_mov_b64 s[2:3], 0
	v_lshrrev_b32_e32 v2, 2, v130
	v_lshrrev_b32_e32 v131, 4, v130
	v_and_b32_e32 v2, 2, v2
	v_lshlrev_b32_e32 v0, 6, v130
	v_bitop3_b32 v2, v131, v2, 3 bitop3:0x6c
	v_bfe_u32 v133, v130, 6, 1
	v_and_b32_e32 v1, 0x3c0, v0
	v_lshlrev_b32_e32 v2, 4, v2
	v_and_b32_e32 v135, 0xffffe000, v0
	v_mov_b32_e32 v0, 0
	v_bfe_u32 v132, v130, 4, 2
	v_add3_u32 v134, 0, v1, v2
	v_lshlrev_b32_e32 v128, 12, v133
	s_mov_b32 s4, s43
	v_mov_b32_e32 v1, v0
	v_mov_b32_e32 v2, v0
	v_mov_b32_e32 v3, v0
	v_mov_b32_e32 v4, v0
	v_mov_b32_e32 v5, v0
	v_mov_b32_e32 v6, v0
	v_mov_b32_e32 v7, v0
	v_mov_b32_e32 v8, v0
	v_mov_b32_e32 v9, v0
	v_mov_b32_e32 v10, v0
	v_mov_b32_e32 v11, v0
	v_mov_b32_e32 v12, v0
	v_mov_b32_e32 v13, v0
	v_mov_b32_e32 v14, v0
	v_mov_b32_e32 v15, v0
	v_mov_b32_e32 v16, v0
	v_mov_b32_e32 v17, v0
	v_mov_b32_e32 v18, v0
	v_mov_b32_e32 v19, v0
	v_mov_b32_e32 v20, v0
	v_mov_b32_e32 v21, v0
	v_mov_b32_e32 v22, v0
	v_mov_b32_e32 v23, v0
	v_mov_b32_e32 v24, v0
	v_mov_b32_e32 v25, v0
	v_mov_b32_e32 v26, v0
	v_mov_b32_e32 v27, v0
	v_mov_b32_e32 v28, v0
	v_mov_b32_e32 v29, v0
	v_mov_b32_e32 v30, v0
	v_mov_b32_e32 v31, v0
	v_mov_b32_e32 v32, v0
	v_mov_b32_e32 v33, v0
	v_mov_b32_e32 v34, v0
	v_mov_b32_e32 v35, v0
	v_mov_b32_e32 v36, v0
	v_mov_b32_e32 v37, v0
	v_mov_b32_e32 v38, v0
	v_mov_b32_e32 v39, v0
	v_mov_b32_e32 v40, v0
	v_mov_b32_e32 v41, v0
	v_mov_b32_e32 v42, v0
	v_mov_b32_e32 v43, v0
	v_mov_b32_e32 v44, v0
	v_mov_b32_e32 v45, v0
	v_mov_b32_e32 v46, v0
	v_mov_b32_e32 v47, v0
	v_mov_b32_e32 v48, v0
	v_mov_b32_e32 v49, v0
	v_mov_b32_e32 v50, v0
	v_mov_b32_e32 v51, v0
	v_mov_b32_e32 v52, v0
	v_mov_b32_e32 v53, v0
	v_mov_b32_e32 v54, v0
	v_mov_b32_e32 v55, v0
	v_mov_b32_e32 v56, v0
	v_mov_b32_e32 v57, v0
	v_mov_b32_e32 v58, v0
	v_mov_b32_e32 v59, v0
	v_mov_b32_e32 v60, v0
	v_mov_b32_e32 v61, v0
	v_mov_b32_e32 v62, v0
	v_mov_b32_e32 v63, v0
	v_mov_b32_e32 v64, v0
	v_mov_b32_e32 v65, v0
	v_mov_b32_e32 v66, v0
	v_mov_b32_e32 v67, v0
	v_mov_b32_e32 v68, v0
	v_mov_b32_e32 v69, v0
	v_mov_b32_e32 v70, v0
	v_mov_b32_e32 v71, v0
	v_mov_b32_e32 v72, v0
	v_mov_b32_e32 v73, v0
	v_mov_b32_e32 v74, v0
	v_mov_b32_e32 v75, v0
	v_mov_b32_e32 v76, v0
	v_mov_b32_e32 v77, v0
	v_mov_b32_e32 v78, v0
	v_mov_b32_e32 v79, v0
	v_mov_b32_e32 v80, v0
	v_mov_b32_e32 v81, v0
	v_mov_b32_e32 v82, v0
	v_mov_b32_e32 v83, v0
	v_mov_b32_e32 v84, v0
	v_mov_b32_e32 v85, v0
	v_mov_b32_e32 v86, v0
	v_mov_b32_e32 v87, v0
	v_mov_b32_e32 v96, v0
	v_mov_b32_e32 v97, v0
	v_mov_b32_e32 v98, v0
	v_mov_b32_e32 v99, v0
	v_mov_b32_e32 v108, v0
	v_mov_b32_e32 v109, v0
	v_mov_b32_e32 v110, v0
	v_mov_b32_e32 v111, v0
	v_mov_b32_e32 v112, v0
	v_mov_b32_e32 v113, v0
	v_mov_b32_e32 v114, v0
	v_mov_b32_e32 v115, v0
	v_mov_b32_e32 v116, v0
	v_mov_b32_e32 v117, v0
	v_mov_b32_e32 v118, v0
	v_mov_b32_e32 v119, v0
	v_mov_b32_e32 v120, v0
	v_mov_b32_e32 v121, v0
	v_mov_b32_e32 v122, v0
	v_mov_b32_e32 v123, v0
	v_mov_b32_e32 v124, v0
	v_mov_b32_e32 v125, v0
	v_mov_b32_e32 v126, v0
	v_mov_b32_e32 v127, v0
	v_mov_b32_e32 v88, v0
	v_mov_b32_e32 v89, v0
	v_mov_b32_e32 v90, v0
	v_mov_b32_e32 v91, v0
	v_mov_b32_e32 v92, v0
	v_mov_b32_e32 v93, v0
	v_mov_b32_e32 v94, v0
	v_mov_b32_e32 v95, v0
	v_mov_b32_e32 v100, v0
	v_mov_b32_e32 v101, v0
	v_mov_b32_e32 v102, v0
	v_mov_b32_e32 v103, v0
	v_mov_b32_e32 v104, v0
	v_mov_b32_e32 v105, v0
	v_mov_b32_e32 v106, v0
	v_mov_b32_e32 v107, v0
	v_and_b32_e32 v224, 3, v172
	v_lshrrev_b32_e32 v225, 4, v172
	v_bitop3_b32 v224, v225, v224, 2 bitop3:0x6c
	v_ashrrev_i32_e32 v225, 6, v172
	v_bfe_u32 v222, v172, 2, 4
	v_readfirstlane_b32 s32, v225
	v_lshl_or_b32 v222, v225, 4, v222
	v_lshlrev_b32_e32 v222, 11, v222
	v_lshl_or_b32 v222, v224, 4, v222
	v_mov_b32_e32 v223, 0
	s_lshl_b32 s32, s32, 10
	v_lshl_add_u64 v[208:209], s[96:97], 0, v[222:223]
	v_lshl_add_u64 v[208:209], v[208:209], 0, s[6:7]
	v_lshl_add_u64 v[210:211], s[96:97], 0, v[222:223]
	v_lshl_add_u64 v[210:211], v[210:211], 0, s[8:9]
	v_lshl_add_u64 v[212:213], s[96:97], 0, v[222:223]
	v_lshl_add_u64 v[212:213], v[212:213], 0, s[10:11]
	v_lshl_add_u64 v[214:215], s[96:97], 0, v[222:223]
	v_lshl_add_u64 v[214:215], v[214:215], 0, s[12:13]
	v_lshl_add_u64 v[218:219], s[92:93], 0, v[222:223]
	v_lshl_add_u64 v[218:219], v[218:219], 0, s[6:7]
	v_lshl_add_u64 v[220:221], s[92:93], 0, v[222:223]
	v_lshl_add_u64 v[220:221], v[220:221], 0, s[8:9]
; template <bool TRANS, class Epi>
; DEVI int g2_body(const G2Tile& t, int st, char* smem, bool has_next, const G2Tile& nxt, const Epi& epi) {
;     ...
;     for (int kt = 0; kt < nk; ++kt) {
;         if (kt + 1 < nk) asm volatile("s_waitcnt vmcnt(6)" ::: "memory");
;         else asm volatile("s_waitcnt vmcnt(0)" ::: "memory");
;         __syncthreads();
;         if (kt + 2 < nk) g2_issue(t, kt + 2, st >= 1 ? st - 1 : 2, smem);
;         const char* sa = smem + st * 24576 + frag;
;         bf16x8 bfr[4];
; #pragma unroll
;         for (int n = 0; n < 4; ++n) bfr[n] = *(const bf16x8*)(sa + (16 + wc * 4 + n) * 1024);
; #pragma unroll
;         for (int mh = 0; mh < 2; ++mh) {
;             bf16x8 af[4];
; #pragma unroll
;             for (int m = 0; m < 4; ++m) af[m] = *(const bf16x8*)(sa + (wr * 8 + mh * 4 + m) * 1024);
;             __builtin_amdgcn_s_setprio(1);
; #pragma unroll
;             for (int m = 0; m < 4; ++m)
; #pragma unroll
;                 for (int n = 0; n < 4; ++n)
;                     acc[mh * 4 + m][n] = TRANS ? __builtin_amdgcn_mfma_f32_16x16x32_bf16(bfr[n], af[m], acc[mh * 4 + m][n], 0, 0, 0)
;                                                : __builtin_amdgcn_mfma_f32_16x16x32_bf16(af[m], bfr[n], acc[mh * 4 + m][n], 0, 0, 0);
;             __builtin_amdgcn_s_setprio(0);
;         }
;         st = st == 2 ? 0 : st + 1;
;     }
.LBB0_243:
	s_waitcnt vmcnt(6)
	s_waitcnt lgkmcnt(0)
	s_barrier
	s_mul_i32 s5, s4, 0x6000
	s_add_i32 s16, s5, 0xffffa000
	s_cmp_gt_i32 s4, 0
	s_cselect_b32 s16, s16, 0xc000
	s_add_i32 s16, s16, s32
	v_add_u32_e32 v152, s5, v134
	v_add_u32_e32 v148, v152, v128
	v_add_u32_e32 v168, v152, v135
	ds_read_b128 v[136:139], v148 offset:16384
	ds_read_b128 v[140:143], v148 offset:17408
	ds_read_b128 v[144:147], v148 offset:18432
	ds_read_b128 v[148:151], v148 offset:19456
	ds_read_b128 v[152:155], v168
	ds_read_b128 v[156:159], v168 offset:1024
	ds_read_b128 v[160:163], v168 offset:2048
	ds_read_b128 v[164:167], v168 offset:3072
	ds_read_b128 v[192:195], v168 offset:4096
	ds_read_b128 v[196:199], v168 offset:5120
	ds_read_b128 v[200:203], v168 offset:6144
	ds_read_b128 v[204:207], v168 offset:7168
	s_mov_b32 m0, s16
	s_nop 0
	global_load_lds_dwordx4 v[208:209], off
	v_lshl_add_u64 v[208:209], v[208:209], 0, 64
	s_add_i32 m0, s16, 0x1000
	s_setprio 1
	s_waitcnt lgkmcnt(7)
	v_mfma_f32_16x16x32_bf16 v[124:127], v[136:139], v[152:155], v[124:127]
	v_mfma_f32_16x16x32_bf16 v[120:123], v[140:143], v[152:155], v[120:123]
	v_mfma_f32_16x16x32_bf16 v[116:119], v[144:147], v[152:155], v[116:119]
	v_mfma_f32_16x16x32_bf16 v[112:115], v[148:151], v[152:155], v[112:115]
	global_load_lds_dwordx4 v[210:211], off
	v_lshl_add_u64 v[210:211], v[210:211], 0, 64
	s_add_i32 m0, s16, 0x2000
	s_waitcnt lgkmcnt(6)
	v_mfma_f32_16x16x32_bf16 v[108:111], v[136:139], v[156:159], v[108:111]
	v_mfma_f32_16x16x32_bf16 v[96:99], v[140:143], v[156:159], v[96:99]
	v_mfma_f32_16x16x32_bf16 v[84:87], v[144:147], v[156:159], v[84:87]
	v_mfma_f32_16x16x32_bf16 v[80:83], v[148:151], v[156:159], v[80:83]
	global_load_lds_dwordx4 v[212:213], off
	v_lshl_add_u64 v[212:213], v[212:213], 0, 64
	s_add_i32 m0, s16, 0x3000
	s_waitcnt lgkmcnt(5)
	v_mfma_f32_16x16x32_bf16 v[76:79], v[136:139], v[160:163], v[76:79]
	v_mfma_f32_16x16x32_bf16 v[72:75], v[140:143], v[160:163], v[72:75]
	v_mfma_f32_16x16x32_bf16 v[68:71], v[144:147], v[160:163], v[68:71]
	v_mfma_f32_16x16x32_bf16 v[64:67], v[148:151], v[160:163], v[64:67]
	global_load_lds_dwordx4 v[214:215], off
	v_lshl_add_u64 v[214:215], v[214:215], 0, 64
	s_add_i32 m0, s16, 0x4000
	s_waitcnt lgkmcnt(4)
	v_mfma_f32_16x16x32_bf16 v[60:63], v[136:139], v[164:167], v[60:63]
	v_mfma_f32_16x16x32_bf16 v[56:59], v[140:143], v[164:167], v[56:59]
	v_mfma_f32_16x16x32_bf16 v[52:55], v[144:147], v[164:167], v[52:55]
	v_mfma_f32_16x16x32_bf16 v[48:51], v[148:151], v[164:167], v[48:51]
	global_load_lds_dwordx4 v[218:219], off
	v_lshl_add_u64 v[218:219], v[218:219], 0, 64
	s_add_i32 m0, s16, 0x5000
	s_waitcnt lgkmcnt(3)
	v_mfma_f32_16x16x32_bf16 v[44:47], v[136:139], v[192:195], v[44:47]
	v_mfma_f32_16x16x32_bf16 v[40:43], v[140:143], v[192:195], v[40:43]
	v_mfma_f32_16x16x32_bf16 v[36:39], v[144:147], v[192:195], v[36:39]
	v_mfma_f32_16x16x32_bf16 v[32:35], v[148:151], v[192:195], v[32:35]
	global_load_lds_dwordx4 v[220:221], off
	v_lshl_add_u64 v[220:221], v[220:221], 0, 64
	s_waitcnt lgkmcnt(2)
	v_mfma_f32_16x16x32_bf16 v[28:31], v[136:139], v[196:199], v[28:31]
	v_mfma_f32_16x16x32_bf16 v[24:27], v[140:143], v[196:199], v[24:27]
	v_mfma_f32_16x16x32_bf16 v[20:23], v[144:147], v[196:199], v[20:23]
	v_mfma_f32_16x16x32_bf16 v[16:19], v[148:151], v[196:199], v[16:19]
	s_waitcnt lgkmcnt(1)
	v_mfma_f32_16x16x32_bf16 v[12:15], v[136:139], v[200:203], v[12:15]
	v_mfma_f32_16x16x32_bf16 v[8:11], v[140:143], v[200:203], v[8:11]
	v_mfma_f32_16x16x32_bf16 v[4:7], v[144:147], v[200:203], v[4:7]
	v_mfma_f32_16x16x32_bf16 v[0:3], v[148:151], v[200:203], v[0:3]
	s_waitcnt lgkmcnt(0)
	v_mfma_f32_16x16x32_bf16 v[88:91], v[136:139], v[204:207], v[88:91]
	v_mfma_f32_16x16x32_bf16 v[92:95], v[140:143], v[204:207], v[92:95]
	v_mfma_f32_16x16x32_bf16 v[100:103], v[144:147], v[204:207], v[100:103]
	v_mfma_f32_16x16x32_bf16 v[104:107], v[148:151], v[204:207], v[104:107]
	s_setprio 0
	s_add_i32 s5, s4, 1
	s_cmp_lg_u32 s4, 2
	s_cselect_b32 s4, s5, 0
	s_add_u32 s2, s2, 64
	s_addc_u32 s3, s3, 0
	s_cmpk_eq_i32 s2, 0x780
	s_cbranch_scc0 .LBB0_243
	s_mul_i32 s2, s4, 0x6000
	v_add_u32_e32 v152, s2, v134
	v_add_u32_e32 v148, v152, v128
	v_add_u32_e32 v168, v152, v135
	s_waitcnt vmcnt(6)
	s_waitcnt vmcnt(0)
	s_barrier
; template <bool TRANS, class Epi>
; DEVI int g2_body(const G2Tile& t, int st, char* smem, bool has_next, const G2Tile& nxt, const Epi& epi) {
;     ...
;     for (int kt = 0; kt < nk; ++kt) {
;         if (kt + 1 < nk) asm volatile("s_waitcnt vmcnt(6)" ::: "memory");
;         else asm volatile("s_waitcnt vmcnt(0)" ::: "memory");
;         __syncthreads();
;         if (kt + 2 < nk) g2_issue(t, kt + 2, st >= 1 ? st - 1 : 2, smem);
;         const char* sa = smem + st * 24576 + frag;
;         bf16x8 bfr[4];
; #pragma unroll
;         for (int n = 0; n < 4; ++n) bfr[n] = *(const bf16x8*)(sa + (16 + wc * 4 + n) * 1024);
; #pragma unroll
;         for (int mh = 0; mh < 2; ++mh) {
;             bf16x8 af[4];
; #pragma unroll
;             for (int m = 0; m < 4; ++m) af[m] = *(const bf16x8*)(sa + (wr * 8 + mh * 4 + m) * 1024);
;             __builtin_amdgcn_s_setprio(1);
; #pragma unroll
;             for (int m = 0; m < 4; ++m)
; #pragma unroll
;                 for (int n = 0; n < 4; ++n)
;                     acc[mh * 4 + m][n] = TRANS ? __builtin_amdgcn_mfma_f32_16x16x32_bf16(bfr[n], af[m], acc[mh * 4 + m][n], 0, 0, 0)
;                                                : __builtin_amdgcn_mfma_f32_16x16x32_bf16(af[m], bfr[n], acc[mh * 4 + m][n], 0, 0, 0);
;             __builtin_amdgcn_s_setprio(0);
;         }
;         st = st == 2 ? 0 : st + 1;
;     }
;     if (has_next) g2_prologue(nxt, st, smem);
	ds_read_b128 v[136:139], v148 offset:16384
	ds_read_b128 v[140:143], v148 offset:17408
	ds_read_b128 v[144:147], v148 offset:18432
	ds_read_b128 v[148:151], v148 offset:19456
	ds_read_b128 v[152:155], v168
	ds_read_b128 v[156:159], v168 offset:1024
	ds_read_b128 v[160:163], v168 offset:2048
	ds_read_b128 v[164:167], v168 offset:3072
	s_setprio 1
	s_waitcnt lgkmcnt(3)
	v_mfma_f32_16x16x32_bf16 v[124:127], v[136:139], v[152:155], v[124:127]
	v_mfma_f32_16x16x32_bf16 v[120:123], v[140:143], v[152:155], v[120:123]
	v_mfma_f32_16x16x32_bf16 v[116:119], v[144:147], v[152:155], v[116:119]
	v_mfma_f32_16x16x32_bf16 v[112:115], v[148:151], v[152:155], v[112:115]
	s_waitcnt lgkmcnt(2)
	v_mfma_f32_16x16x32_bf16 v[108:111], v[136:139], v[156:159], v[108:111]
	v_mfma_f32_16x16x32_bf16 v[96:99], v[140:143], v[156:159], v[96:99]
	v_mfma_f32_16x16x32_bf16 v[84:87], v[144:147], v[156:159], v[84:87]
	v_mfma_f32_16x16x32_bf16 v[80:83], v[148:151], v[156:159], v[80:83]
	s_waitcnt lgkmcnt(1)
	v_mfma_f32_16x16x32_bf16 v[76:79], v[136:139], v[160:163], v[76:79]
	v_mfma_f32_16x16x32_bf16 v[72:75], v[140:143], v[160:163], v[72:75]
	v_mfma_f32_16x16x32_bf16 v[68:71], v[144:147], v[160:163], v[68:71]
	v_mfma_f32_16x16x32_bf16 v[64:67], v[148:151], v[160:163], v[64:67]
	s_waitcnt lgkmcnt(0)
	v_mfma_f32_16x16x32_bf16 v[60:63], v[136:139], v[164:167], v[60:63]
	v_mfma_f32_16x16x32_bf16 v[56:59], v[140:143], v[164:167], v[56:59]
	v_mfma_f32_16x16x32_bf16 v[52:55], v[144:147], v[164:167], v[52:55]
	v_mfma_f32_16x16x32_bf16 v[48:51], v[148:151], v[164:167], v[48:51]
	s_setprio 0
	ds_read_b128 v[152:155], v168 offset:4096
	ds_read_b128 v[156:159], v168 offset:5120
	ds_read_b128 v[160:163], v168 offset:6144
	ds_read_b128 v[164:167], v168 offset:7168
	s_setprio 1
	s_waitcnt lgkmcnt(3)
	v_mfma_f32_16x16x32_bf16 v[44:47], v[136:139], v[152:155], v[44:47]
	v_mfma_f32_16x16x32_bf16 v[40:43], v[140:143], v[152:155], v[40:43]
	v_mfma_f32_16x16x32_bf16 v[36:39], v[144:147], v[152:155], v[36:39]
	v_mfma_f32_16x16x32_bf16 v[32:35], v[148:151], v[152:155], v[32:35]
	s_waitcnt lgkmcnt(2)
	v_mfma_f32_16x16x32_bf16 v[28:31], v[136:139], v[156:159], v[28:31]
	v_mfma_f32_16x16x32_bf16 v[24:27], v[140:143], v[156:159], v[24:27]
	v_mfma_f32_16x16x32_bf16 v[20:23], v[144:147], v[156:159], v[20:23]
	v_mfma_f32_16x16x32_bf16 v[16:19], v[148:151], v[156:159], v[16:19]
	s_waitcnt lgkmcnt(1)
	v_mfma_f32_16x16x32_bf16 v[12:15], v[136:139], v[160:163], v[12:15]
	v_mfma_f32_16x16x32_bf16 v[8:11], v[140:143], v[160:163], v[8:11]
	v_mfma_f32_16x16x32_bf16 v[4:7], v[144:147], v[160:163], v[4:7]
	v_mfma_f32_16x16x32_bf16 v[0:3], v[148:151], v[160:163], v[0:3]
	s_waitcnt lgkmcnt(0)
	v_mfma_f32_16x16x32_bf16 v[136:139], v[136:139], v[164:167], v[88:91]
	v_mfma_f32_16x16x32_bf16 v[140:143], v[140:143], v[164:167], v[92:95]
	v_mfma_f32_16x16x32_bf16 v[144:147], v[144:147], v[164:167], v[100:103]
	v_mfma_f32_16x16x32_bf16 v[148:151], v[148:151], v[164:167], v[104:107]
	s_setprio 0
	s_add_i32 s2, s4, 1
	s_cmp_lg_u32 s4, 2
	s_cselect_b32 s2, s2, 0
	s_mul_i32 s3, s2, 0x6000
	v_add_u32_e32 v100, s3, v134
	v_add_u32_e32 v134, v100, v135
	v_add_u32_e32 v100, v100, v128
	s_waitcnt vmcnt(0)
	s_barrier
	ds_read_b128 v[152:155], v134 offset:3072
	ds_read_b128 v[156:159], v134 offset:2048
	ds_read_b128 v[88:91], v134 offset:1024
	ds_read_b128 v[92:95], v134
	ds_read_b128 v[160:163], v100 offset:19456
	ds_read_b128 v[164:167], v100 offset:18432
	ds_read_b128 v[168:171], v100 offset:17408
	ds_read_b128 v[184:187], v100 offset:16384
	s_setprio 1
	s_waitcnt lgkmcnt(0)
	v_mfma_f32_16x16x32_bf16 v[124:127], v[184:187], v[92:95], v[124:127]
	v_mfma_f32_16x16x32_bf16 v[120:123], v[168:171], v[92:95], v[120:123]
	v_mfma_f32_16x16x32_bf16 v[116:119], v[164:167], v[92:95], v[116:119]
	v_mfma_f32_16x16x32_bf16 v[112:115], v[160:163], v[92:95], v[112:115]
	v_mfma_f32_16x16x32_bf16 v[108:111], v[184:187], v[88:91], v[108:111]
	v_mfma_f32_16x16x32_bf16 v[104:107], v[168:171], v[88:91], v[96:99]
	v_mfma_f32_16x16x32_bf16 v[100:103], v[164:167], v[88:91], v[84:87]
	v_mfma_f32_16x16x32_bf16 v[96:99], v[160:163], v[88:91], v[80:83]
	v_mfma_f32_16x16x32_bf16 v[92:95], v[184:187], v[156:159], v[76:79]
	v_mfma_f32_16x16x32_bf16 v[88:91], v[168:171], v[156:159], v[72:75]
	v_mfma_f32_16x16x32_bf16 v[84:87], v[164:167], v[156:159], v[68:71]
	v_mfma_f32_16x16x32_bf16 v[80:83], v[160:163], v[156:159], v[64:67]
	v_mfma_f32_16x16x32_bf16 v[76:79], v[184:187], v[152:155], v[60:63]
	v_mfma_f32_16x16x32_bf16 v[72:75], v[168:171], v[152:155], v[56:59]
	v_mfma_f32_16x16x32_bf16 v[68:71], v[164:167], v[152:155], v[52:55]
	v_mfma_f32_16x16x32_bf16 v[64:67], v[160:163], v[152:155], v[48:51]
	s_setprio 0
	s_nop 1
	ds_read_b128 v[48:51], v134 offset:4096
	ds_read_b128 v[152:155], v134 offset:5120
	ds_read_b128 v[156:159], v134 offset:6144
	ds_read_b128 v[188:191], v134 offset:7168
	s_setprio 1
	s_waitcnt lgkmcnt(3)
	v_mfma_f32_16x16x32_bf16 v[60:63], v[184:187], v[48:51], v[44:47]
	v_mfma_f32_16x16x32_bf16 v[56:59], v[168:171], v[48:51], v[40:43]
	v_mfma_f32_16x16x32_bf16 v[52:55], v[164:167], v[48:51], v[36:39]
	v_mfma_f32_16x16x32_bf16 v[48:51], v[160:163], v[48:51], v[32:35]
	s_waitcnt lgkmcnt(2)
	v_mfma_f32_16x16x32_bf16 v[44:47], v[184:187], v[152:155], v[28:31]
	v_mfma_f32_16x16x32_bf16 v[40:43], v[168:171], v[152:155], v[24:27]
	v_mfma_f32_16x16x32_bf16 v[36:39], v[164:167], v[152:155], v[20:23]
	v_mfma_f32_16x16x32_bf16 v[32:35], v[160:163], v[152:155], v[16:19]
	s_waitcnt lgkmcnt(1)
	v_mfma_f32_16x16x32_bf16 v[28:31], v[184:187], v[156:159], v[12:15]
	v_mfma_f32_16x16x32_bf16 v[24:27], v[168:171], v[156:159], v[8:11]
	v_mfma_f32_16x16x32_bf16 v[20:23], v[164:167], v[156:159], v[4:7]
	v_mfma_f32_16x16x32_bf16 v[16:19], v[160:163], v[156:159], v[0:3]
	s_waitcnt lgkmcnt(0)
	v_mfma_f32_16x16x32_bf16 v[12:15], v[184:187], v[188:191], v[136:139]
	v_mfma_f32_16x16x32_bf16 v[8:11], v[168:171], v[188:191], v[140:143]
	v_mfma_f32_16x16x32_bf16 v[4:7], v[164:167], v[188:191], v[144:147]
	v_mfma_f32_16x16x32_bf16 v[0:3], v[160:163], v[188:191], v[148:151]
	s_setprio 0
	s_add_i32 s3, s2, 1
	s_cmp_lg_u32 s2, 2
	s_cselect_b32 s50, s3, 0
	s_and_b64 vcc, exec, s[30:31]
	s_cbranch_vccz .LBB0_246
; DEVI int opaque_tid() { int t = (int)threadIdx.x; asm volatile("" : "+v"(t)); return t; }
; DEVI void g2_issue(const G2Tile& t, int kt, int st, char* smem) {
;     const int tid = opaque_tid(), lane = tid & 63, w = tid >> 6;
;     const int rr = lane >> 2, sch = (lane & 3) ^ ((lane >> 5) << 1);
;     const bf16_t* ap = t.A + (size_t)kt * 32 + (size_t)(w * 16 + rr) * t.lda + sch * 8;
;     const bf16_t* bp = t.Bt + (size_t)kt * 32 + (size_t)(w * 16 + rr) * t.ldb + sch * 8;
;     char* sa = smem + st * 24576 + w * 1024 + lane * 16;
; #pragma unroll
;     for (int i = 0; i < 4; ++i) __builtin_amdgcn_global_load_lds((const unsigned*)(ap + (size_t)(64 * i) * t.lda), (unsigned*)(sa + i * 4096), 16, 0, 0);
; #pragma unroll
;     for (int i = 0; i < 2; ++i) __builtin_amdgcn_global_load_lds((const unsigned*)(bp + (size_t)(64 * i) * t.ldb), (unsigned*)(sa + 16384 + i * 4096), 16, 0, 0);
; }
; DEVI void g2_prologue(const G2Tile& t, int st, char* smem) {
;     g2_issue(t, 0, st, smem);
;     g2_issue(t, 1, st == 2 ? 0 : st + 1, smem);
; }
	v_mov_b32_e32 v128, v172
	s_mul_i32 s2, s50, 0x6000
	v_ashrrev_i32_e32 v139, 6, v128
	v_bfe_u32 v134, v128, 2, 4
	v_and_b32_e32 v138, 63, v128
	v_and_b32_e32 v135, 3, v128
	v_lshrrev_b32_e32 v128, 4, v128
	v_lshl_or_b32 v134, v139, 4, v134
	v_bitop3_b32 v128, v128, v135, 2 bitop3:0x6c
	v_ashrrev_i32_e32 v135, 31, v134
	s_add_i32 s3, s2, 0
	v_lshlrev_b32_e32 v139, 10, v139
	v_lshlrev_b32_e32 v138, 4, v138
	v_lshlrev_b64 v[134:135], 11, v[134:135]
	v_add3_u32 v140, s3, v139, v138
	v_lshl_add_u64 v[136:137], s[0:1], 0, v[134:135]
	v_lshlrev_b32_e32 v128, 4, v128
	v_readfirstlane_b32 s3, v140
	v_add_u32_e32 v141, 0x1000, v140
	v_lshl_add_u64 v[136:137], v[136:137], 0, v[128:129]
	s_mov_b32 m0, s3
	v_readfirstlane_b32 s3, v141
	v_add_u32_e32 v141, 0x2000, v140
	global_load_lds_dwordx4 v[136:137], off
	v_lshl_add_u64 v[138:139], v[136:137], 0, s[22:23]
	s_mov_b32 m0, s3
	v_readfirstlane_b32 s3, v141
	global_load_lds_dwordx4 v[138:139], off
	v_lshl_add_u64 v[138:139], v[136:137], 0, s[24:25]
	s_mov_b32 m0, s3
	v_lshl_add_u64 v[134:135], s[20:21], 0, v[134:135]
	global_load_lds_dwordx4 v[138:139], off
	v_add_u32_e32 v138, 0x3000, v140
	v_lshl_add_u64 v[134:135], v[134:135], 0, v[128:129]
	v_readfirstlane_b32 s3, v138
	v_add_u32_e32 v128, 0x4000, v140
	v_lshl_add_u64 v[136:137], v[136:137], 0, s[28:29]
	s_mov_b32 m0, s3
	v_readfirstlane_b32 s3, v128
	v_add_u32_e32 v128, 0x5000, v140
	global_load_lds_dwordx4 v[136:137], off
	s_mov_b32 m0, s3
	v_readfirstlane_b32 s3, v128
	global_load_lds_dwordx4 v[134:135], off
	v_lshl_add_u64 v[134:135], v[134:135], 0, s[22:23]
	s_mov_b32 m0, s3
	v_mov_b32_e32 v128, v172
	global_load_lds_dwordx4 v[134:135], off
	s_addk_i32 s2, 0x6000
	v_ashrrev_i32_e32 v141, 6, v128
	v_bfe_u32 v134, v128, 2, 4
	v_and_b32_e32 v140, 63, v128
	v_and_b32_e32 v135, 3, v128
	v_lshrrev_b32_e32 v128, 4, v128
	v_lshl_or_b32 v134, v141, 4, v134
	s_cmp_lg_u32 s50, 2
	v_bitop3_b32 v128, v128, v135, 2 bitop3:0x6c
	v_ashrrev_i32_e32 v135, 31, v134
	s_cselect_b32 s2, s2, 0
	v_lshlrev_b64 v[134:135], 11, v[134:135]
	s_add_i32 s2, s2, 0
	v_lshlrev_b32_e32 v141, 10, v141
	v_lshlrev_b32_e32 v140, 4, v140
	v_lshl_add_u64 v[136:137], s[0:1], 0, v[134:135]
	v_lshlrev_b32_e32 v128, 4, v128
	v_add3_u32 v140, s2, v141, v140
	v_lshl_add_u64 v[136:137], v[136:137], 0, v[128:129]
	v_readfirstlane_b32 s2, v140
	v_add_u32_e32 v141, 0x1000, v140
	v_lshl_add_u64 v[138:139], v[136:137], 0, 64
	s_mov_b32 m0, s2
	v_readfirstlane_b32 s2, v141
	v_add_u32_e32 v141, 0x2000, v140
	global_load_lds_dwordx4 v[138:139], off
	v_lshl_add_u64 v[138:139], v[136:137], 0, s[58:59]
	s_mov_b32 m0, s2
	v_readfirstlane_b32 s2, v141
	global_load_lds_dwordx4 v[138:139], off
	v_lshl_add_u64 v[138:139], v[136:137], 0, s[60:61]
	s_mov_b32 m0, s2
	v_lshl_add_u64 v[134:135], s[20:21], 0, v[134:135]
	global_load_lds_dwordx4 v[138:139], off
	v_add_u32_e32 v138, 0x3000, v140
	v_lshl_add_u64 v[134:135], v[134:135], 0, v[128:129]
	v_readfirstlane_b32 s2, v138
	v_add_u32_e32 v128, 0x4000, v140
	v_lshl_add_u64 v[136:137], v[136:137], 0, s[62:63]
	s_mov_b32 m0, s2
	v_readfirstlane_b32 s2, v128
	v_add_u32_e32 v128, 0x5000, v140
	global_load_lds_dwordx4 v[136:137], off
	v_lshl_add_u64 v[136:137], v[134:135], 0, 64
	s_mov_b32 m0, s2
	v_readfirstlane_b32 s2, v128
	global_load_lds_dwordx4 v[136:137], off
	v_lshl_add_u64 v[134:135], v[134:135], 0, s[58:59]
	s_mov_b32 m0, s2
	s_nop 0
	global_load_lds_dwordx4 v[134:135], off

; DEVI int opaque_tid() { int t = (int)threadIdx.x; asm volatile("" : "+v"(t)); return t; }
; DEVI void g2_issue(const G2Tile& t, int kt, int st, char* smem) {
;     const int tid = opaque_tid(), lane = tid & 63, w = tid >> 6;
;     const int rr = lane >> 2, sch = (lane & 3) ^ ((lane >> 5) << 1);
;     const bf16_t* ap = t.A + (size_t)kt * 32 + (size_t)(w * 16 + rr) * t.lda + sch * 8;
;     const bf16_t* bp = t.Bt + (size_t)kt * 32 + (size_t)(w * 16 + rr) * t.ldb + sch * 8;
;     char* sa = smem + st * 24576 + w * 1024 + lane * 16;
; #pragma unroll
;     for (int i = 0; i < 4; ++i) __builtin_amdgcn_global_load_lds((const unsigned*)(ap + (size_t)(64 * i) * t.lda), (unsigned*)(sa + i * 4096), 16, 0, 0);
; #pragma unroll
;     for (int i = 0; i < 2; ++i) __builtin_amdgcn_global_load_lds((const unsigned*)(bp + (size_t)(64 * i) * t.ldb), (unsigned*)(sa + 16384 + i * 4096), 16, 0, 0);
; }
; DEVI void g2_prologue(const G2Tile& t, int st, char* smem) {
;     g2_issue(t, 0, st, smem);
;     g2_issue(t, 1, st == 2 ? 0 : st + 1, smem);
; }
; template <bool TRANS, class Epi>
; DEVI int g2_body(const G2Tile& t, int st, char* smem, bool has_next, const G2Tile& nxt, const Epi& epi) {
;     const int tid = opaque_tid(), lane = tid & 63, w = tid >> 6, wr = w >> 1, wc = w & 1, fr = lane & 15, fq = lane >> 4;
;     f32x4 acc[8][4];
; #pragma unroll
;     for (int m = 0; m < 8; ++m)
; #pragma unroll
;         for (int n = 0; n < 4; ++n) acc[m][n] = (f32x4){0.f, 0.f, 0.f, 0.f};
;     const int frag = fr * 64 + ((fq ^ ((fr >> 3) << 1)) << 4);
;     const int nk = t.nk;
.LBB0_279:
	s_cbranch_execz .LBB0_234
	v_mov_b32_e32 v133, v172
	s_mov_b64 s[2:3], 0
	v_lshrrev_b32_e32 v2, 2, v133
	v_lshrrev_b32_e32 v0, 4, v133
	v_and_b32_e32 v2, 2, v2
	v_and_b32_e32 v132, 15, v133
	v_bitop3_b32 v0, v0, v2, 3 bitop3:0x6c
	v_lshlrev_b32_e32 v1, 6, v132
	v_lshlrev_b32_e32 v0, 4, v0
	v_add3_u32 v134, 0, v1, v0
	v_lshlrev_b32_e32 v0, 6, v133
	v_bfe_u32 v131, v133, 6, 1
	v_and_b32_e32 v135, 0xffffe000, v0
	v_mov_b32_e32 v0, 0
	v_bfe_u32 v130, v133, 4, 2
	v_lshlrev_b32_e32 v128, 12, v131
	v_mov_b32_e32 v1, v0
	v_mov_b32_e32 v2, v0
	v_mov_b32_e32 v3, v0
	v_mov_b32_e32 v4, v0
	v_mov_b32_e32 v5, v0
	v_mov_b32_e32 v6, v0
	v_mov_b32_e32 v7, v0
	v_mov_b32_e32 v8, v0
	v_mov_b32_e32 v9, v0
	v_mov_b32_e32 v10, v0
	v_mov_b32_e32 v11, v0
	v_mov_b32_e32 v12, v0
	v_mov_b32_e32 v13, v0
	v_mov_b32_e32 v14, v0
	v_mov_b32_e32 v15, v0
	v_mov_b32_e32 v16, v0
	v_mov_b32_e32 v17, v0
	v_mov_b32_e32 v18, v0
	v_mov_b32_e32 v19, v0
	v_mov_b32_e32 v20, v0
	v_mov_b32_e32 v21, v0
	v_mov_b32_e32 v22, v0
	v_mov_b32_e32 v23, v0
	v_mov_b32_e32 v24, v0
	v_mov_b32_e32 v25, v0
	v_mov_b32_e32 v26, v0
	v_mov_b32_e32 v27, v0
	v_mov_b32_e32 v28, v0
	v_mov_b32_e32 v29, v0
	v_mov_b32_e32 v30, v0
	v_mov_b32_e32 v31, v0
	v_mov_b32_e32 v32, v0
	v_mov_b32_e32 v33, v0
	v_mov_b32_e32 v34, v0
	v_mov_b32_e32 v35, v0
	v_mov_b32_e32 v36, v0
	v_mov_b32_e32 v37, v0
	v_mov_b32_e32 v38, v0
	v_mov_b32_e32 v39, v0
	v_mov_b32_e32 v40, v0
	v_mov_b32_e32 v41, v0
	v_mov_b32_e32 v42, v0
	v_mov_b32_e32 v43, v0
	v_mov_b32_e32 v44, v0
	v_mov_b32_e32 v45, v0
	v_mov_b32_e32 v46, v0
	v_mov_b32_e32 v47, v0
	v_mov_b32_e32 v48, v0
	v_mov_b32_e32 v49, v0
	v_mov_b32_e32 v50, v0
	v_mov_b32_e32 v51, v0
	v_mov_b32_e32 v52, v0
	v_mov_b32_e32 v53, v0
	v_mov_b32_e32 v54, v0
	v_mov_b32_e32 v55, v0
	v_mov_b32_e32 v56, v0
	v_mov_b32_e32 v57, v0
	v_mov_b32_e32 v58, v0
	v_mov_b32_e32 v59, v0
	v_mov_b32_e32 v60, v0
	v_mov_b32_e32 v61, v0
	v_mov_b32_e32 v62, v0
	v_mov_b32_e32 v63, v0
	v_mov_b32_e32 v64, v0
	v_mov_b32_e32 v65, v0
	v_mov_b32_e32 v66, v0
	v_mov_b32_e32 v67, v0
	v_mov_b32_e32 v68, v0
	v_mov_b32_e32 v69, v0
	v_mov_b32_e32 v70, v0
	v_mov_b32_e32 v71, v0
	v_mov_b32_e32 v72, v0
	v_mov_b32_e32 v73, v0
	v_mov_b32_e32 v74, v0
	v_mov_b32_e32 v75, v0
	v_mov_b32_e32 v76, v0
	v_mov_b32_e32 v77, v0
	v_mov_b32_e32 v78, v0
	v_mov_b32_e32 v79, v0
	v_mov_b32_e32 v80, v0
	v_mov_b32_e32 v81, v0
	v_mov_b32_e32 v82, v0
	v_mov_b32_e32 v83, v0
	v_mov_b32_e32 v84, v0
	v_mov_b32_e32 v85, v0
	v_mov_b32_e32 v86, v0
	v_mov_b32_e32 v87, v0
	v_mov_b32_e32 v96, v0
	v_mov_b32_e32 v97, v0
	v_mov_b32_e32 v98, v0
	v_mov_b32_e32 v99, v0
	v_mov_b32_e32 v108, v0
	v_mov_b32_e32 v109, v0
	v_mov_b32_e32 v110, v0
	v_mov_b32_e32 v111, v0
	v_mov_b32_e32 v112, v0
	v_mov_b32_e32 v113, v0
	v_mov_b32_e32 v114, v0
	v_mov_b32_e32 v115, v0
	v_mov_b32_e32 v116, v0
	v_mov_b32_e32 v117, v0
	v_mov_b32_e32 v118, v0
	v_mov_b32_e32 v119, v0
	v_mov_b32_e32 v120, v0
	v_mov_b32_e32 v121, v0
	v_mov_b32_e32 v122, v0
	v_mov_b32_e32 v123, v0
	v_mov_b32_e32 v124, v0
	v_mov_b32_e32 v125, v0
	v_mov_b32_e32 v126, v0
	v_mov_b32_e32 v127, v0
	v_mov_b32_e32 v88, v0
	v_mov_b32_e32 v89, v0
	v_mov_b32_e32 v90, v0
	v_mov_b32_e32 v91, v0
	v_mov_b32_e32 v92, v0
	v_mov_b32_e32 v93, v0
	v_mov_b32_e32 v94, v0
	v_mov_b32_e32 v95, v0
	v_mov_b32_e32 v100, v0
	v_mov_b32_e32 v101, v0
	v_mov_b32_e32 v102, v0
	v_mov_b32_e32 v103, v0
	v_mov_b32_e32 v104, v0
	v_mov_b32_e32 v105, v0
	v_mov_b32_e32 v106, v0
	v_mov_b32_e32 v107, v0
	v_and_b32_e32 v224, 3, v172
	v_lshrrev_b32_e32 v225, 4, v172
	v_bitop3_b32 v224, v225, v224, 2 bitop3:0x6c
	v_ashrrev_i32_e32 v225, 6, v172
	v_bfe_u32 v222, v172, 2, 4
	v_readfirstlane_b32 s32, v225
	v_lshl_or_b32 v222, v225, 4, v222
	v_lshlrev_b32_e32 v222, 11, v222
	v_lshl_or_b32 v222, v224, 4, v222
	v_mov_b32_e32 v223, 0
	s_lshl_b32 s32, s32, 10
	v_lshl_add_u64 v[208:209], s[96:97], 0, v[222:223]
	v_lshl_add_u64 v[208:209], v[208:209], 0, s[6:7]
	v_lshl_add_u64 v[210:211], s[96:97], 0, v[222:223]
	v_lshl_add_u64 v[210:211], v[210:211], 0, s[8:9]
	v_lshl_add_u64 v[212:213], s[96:97], 0, v[222:223]
	v_lshl_add_u64 v[212:213], v[212:213], 0, s[10:11]
	v_lshl_add_u64 v[214:215], s[96:97], 0, v[222:223]
	v_lshl_add_u64 v[214:215], v[214:215], 0, s[12:13]
	v_lshl_add_u64 v[218:219], s[92:93], 0, v[222:223]
	v_lshl_add_u64 v[218:219], v[218:219], 0, s[6:7]
	v_lshl_add_u64 v[220:221], s[92:93], 0, v[222:223]
	v_lshl_add_u64 v[220:221], v[220:221], 0, s[8:9]
; template <bool TRANS, class Epi>
; DEVI int g2_body(const G2Tile& t, int st, char* smem, bool has_next, const G2Tile& nxt, const Epi& epi) {
;     ...
;     for (int kt = 0; kt < nk; ++kt) {
;         if (kt + 1 < nk) asm volatile("s_waitcnt vmcnt(6)" ::: "memory");
;         else asm volatile("s_waitcnt vmcnt(0)" ::: "memory");
;         __syncthreads();
;         if (kt + 2 < nk) g2_issue(t, kt + 2, st >= 1 ? st - 1 : 2, smem);
;         const char* sa = smem + st * 24576 + frag;
;         bf16x8 bfr[4];
; #pragma unroll
;         for (int n = 0; n < 4; ++n) bfr[n] = *(const bf16x8*)(sa + (16 + wc * 4 + n) * 1024);
; #pragma unroll
;         for (int mh = 0; mh < 2; ++mh) {
;             bf16x8 af[4];
; #pragma unroll
;             for (int m = 0; m < 4; ++m) af[m] = *(const bf16x8*)(sa + (wr * 8 + mh * 4 + m) * 1024);
;             __builtin_amdgcn_s_setprio(1);
; #pragma unroll
;             for (int m = 0; m < 4; ++m)
; #pragma unroll
;                 for (int n = 0; n < 4; ++n)
;                     acc[mh * 4 + m][n] = TRANS ? __builtin_amdgcn_mfma_f32_16x16x32_bf16(bfr[n], af[m], acc[mh * 4 + m][n], 0, 0, 0)
;                                                : __builtin_amdgcn_mfma_f32_16x16x32_bf16(af[m], bfr[n], acc[mh * 4 + m][n], 0, 0, 0);
;             __builtin_amdgcn_s_setprio(0);
;         }
;         st = st == 2 ? 0 : st + 1;
;     }
.LBB0_281:
	s_waitcnt vmcnt(6)
	s_waitcnt lgkmcnt(0)
	s_barrier
	s_mul_i32 s4, s43, 0x6000
	s_add_i32 s5, s4, 0xffffa000
	s_cmp_gt_i32 s43, 0
	s_cselect_b32 s5, s5, 0xc000
	s_add_i32 s5, s5, s32
	v_add_u32_e32 v152, s4, v134
	v_add_u32_e32 v148, v152, v128
	v_add_u32_e32 v168, v152, v135
	ds_read_b128 v[136:139], v148 offset:16384
	ds_read_b128 v[140:143], v148 offset:17408
	ds_read_b128 v[144:147], v148 offset:18432
	ds_read_b128 v[148:151], v148 offset:19456
	ds_read_b128 v[152:155], v168
	ds_read_b128 v[156:159], v168 offset:1024
	ds_read_b128 v[160:163], v168 offset:2048
	ds_read_b128 v[164:167], v168 offset:3072
	ds_read_b128 v[192:195], v168 offset:4096
	ds_read_b128 v[196:199], v168 offset:5120
	ds_read_b128 v[200:203], v168 offset:6144
	ds_read_b128 v[204:207], v168 offset:7168
	s_mov_b32 m0, s5
	s_nop 0
	global_load_lds_dwordx4 v[208:209], off
	v_lshl_add_u64 v[208:209], v[208:209], 0, 64
	s_add_i32 m0, s5, 0x1000
	s_setprio 1
	s_waitcnt lgkmcnt(7)
	v_mfma_f32_16x16x32_bf16 v[124:127], v[152:155], v[136:139], v[124:127]
	v_mfma_f32_16x16x32_bf16 v[120:123], v[152:155], v[140:143], v[120:123]
	v_mfma_f32_16x16x32_bf16 v[116:119], v[152:155], v[144:147], v[116:119]
	v_mfma_f32_16x16x32_bf16 v[112:115], v[152:155], v[148:151], v[112:115]
	global_load_lds_dwordx4 v[210:211], off
	v_lshl_add_u64 v[210:211], v[210:211], 0, 64
	s_add_i32 m0, s5, 0x2000
	s_waitcnt lgkmcnt(6)
	v_mfma_f32_16x16x32_bf16 v[108:111], v[156:159], v[136:139], v[108:111]
	v_mfma_f32_16x16x32_bf16 v[96:99], v[156:159], v[140:143], v[96:99]
	v_mfma_f32_16x16x32_bf16 v[84:87], v[156:159], v[144:147], v[84:87]
	v_mfma_f32_16x16x32_bf16 v[80:83], v[156:159], v[148:151], v[80:83]
	global_load_lds_dwordx4 v[212:213], off
	v_lshl_add_u64 v[212:213], v[212:213], 0, 64
	s_add_i32 m0, s5, 0x3000
	s_waitcnt lgkmcnt(5)
	v_mfma_f32_16x16x32_bf16 v[76:79], v[160:163], v[136:139], v[76:79]
	v_mfma_f32_16x16x32_bf16 v[72:75], v[160:163], v[140:143], v[72:75]
	v_mfma_f32_16x16x32_bf16 v[68:71], v[160:163], v[144:147], v[68:71]
	v_mfma_f32_16x16x32_bf16 v[64:67], v[160:163], v[148:151], v[64:67]
	global_load_lds_dwordx4 v[214:215], off
	v_lshl_add_u64 v[214:215], v[214:215], 0, 64
	s_add_i32 m0, s5, 0x4000
	s_waitcnt lgkmcnt(4)
	v_mfma_f32_16x16x32_bf16 v[60:63], v[164:167], v[136:139], v[60:63]
	v_mfma_f32_16x16x32_bf16 v[56:59], v[164:167], v[140:143], v[56:59]
	v_mfma_f32_16x16x32_bf16 v[52:55], v[164:167], v[144:147], v[52:55]
	v_mfma_f32_16x16x32_bf16 v[48:51], v[164:167], v[148:151], v[48:51]
	global_load_lds_dwordx4 v[218:219], off
	v_lshl_add_u64 v[218:219], v[218:219], 0, 64
	s_add_i32 m0, s5, 0x5000
	s_waitcnt lgkmcnt(3)
	v_mfma_f32_16x16x32_bf16 v[44:47], v[192:195], v[136:139], v[44:47]
	v_mfma_f32_16x16x32_bf16 v[40:43], v[192:195], v[140:143], v[40:43]
	v_mfma_f32_16x16x32_bf16 v[36:39], v[192:195], v[144:147], v[36:39]
	v_mfma_f32_16x16x32_bf16 v[32:35], v[192:195], v[148:151], v[32:35]
	global_load_lds_dwordx4 v[220:221], off
	v_lshl_add_u64 v[220:221], v[220:221], 0, 64
	s_waitcnt lgkmcnt(2)
	v_mfma_f32_16x16x32_bf16 v[28:31], v[196:199], v[136:139], v[28:31]
	v_mfma_f32_16x16x32_bf16 v[24:27], v[196:199], v[140:143], v[24:27]
	v_mfma_f32_16x16x32_bf16 v[20:23], v[196:199], v[144:147], v[20:23]
	v_mfma_f32_16x16x32_bf16 v[16:19], v[196:199], v[148:151], v[16:19]
	s_waitcnt lgkmcnt(1)
	v_mfma_f32_16x16x32_bf16 v[12:15], v[200:203], v[136:139], v[12:15]
	v_mfma_f32_16x16x32_bf16 v[8:11], v[200:203], v[140:143], v[8:11]
	v_mfma_f32_16x16x32_bf16 v[4:7], v[200:203], v[144:147], v[4:7]
	v_mfma_f32_16x16x32_bf16 v[0:3], v[200:203], v[148:151], v[0:3]
	s_waitcnt lgkmcnt(0)
	v_mfma_f32_16x16x32_bf16 v[88:91], v[204:207], v[136:139], v[88:91]
	v_mfma_f32_16x16x32_bf16 v[92:95], v[204:207], v[140:143], v[92:95]
	v_mfma_f32_16x16x32_bf16 v[100:103], v[204:207], v[144:147], v[100:103]
	v_mfma_f32_16x16x32_bf16 v[104:107], v[204:207], v[148:151], v[104:107]
	s_setprio 0
	s_add_i32 s4, s43, 1
	s_cmp_lg_u32 s43, 2
	s_cselect_b32 s43, s4, 0
	s_add_u32 s2, s2, 64
	s_addc_u32 s3, s3, 0
	s_cmpk_eq_i32 s2, 0x780
	s_cbranch_scc0 .LBB0_281
	s_mul_i32 s2, s43, 0x6000
	v_add_u32_e32 v152, s2, v134
	v_add_u32_e32 v148, v152, v128
	v_add_u32_e32 v168, v152, v135
	s_waitcnt vmcnt(6)
	s_waitcnt vmcnt(0)
	s_barrier
; template <bool TRANS, class Epi>
; DEVI int g2_body(const G2Tile& t, int st, char* smem, bool has_next, const G2Tile& nxt, const Epi& epi) {
;     ...
;     for (int kt = 0; kt < nk; ++kt) {
;         if (kt + 1 < nk) asm volatile("s_waitcnt vmcnt(6)" ::: "memory");
;         else asm volatile("s_waitcnt vmcnt(0)" ::: "memory");
;         __syncthreads();
;         if (kt + 2 < nk) g2_issue(t, kt + 2, st >= 1 ? st - 1 : 2, smem);
;         const char* sa = smem + st * 24576 + frag;
;         bf16x8 bfr[4];
; #pragma unroll
;         for (int n = 0; n < 4; ++n) bfr[n] = *(const bf16x8*)(sa + (16 + wc * 4 + n) * 1024);
; #pragma unroll
;         for (int mh = 0; mh < 2; ++mh) {
;             bf16x8 af[4];
; #pragma unroll
;             for (int m = 0; m < 4; ++m) af[m] = *(const bf16x8*)(sa + (wr * 8 + mh * 4 + m) * 1024);
;             __builtin_amdgcn_s_setprio(1);
; #pragma unroll
;             for (int m = 0; m < 4; ++m)
; #pragma unroll
;                 for (int n = 0; n < 4; ++n)
;                     acc[mh * 4 + m][n] = TRANS ? __builtin_amdgcn_mfma_f32_16x16x32_bf16(bfr[n], af[m], acc[mh * 4 + m][n], 0, 0, 0)
;                                                : __builtin_amdgcn_mfma_f32_16x16x32_bf16(af[m], bfr[n], acc[mh * 4 + m][n], 0, 0, 0);
;             __builtin_amdgcn_s_setprio(0);
;         }
;         st = st == 2 ? 0 : st + 1;
;     }
;     if (has_next) g2_prologue(nxt, st, smem);
	ds_read_b128 v[136:139], v148 offset:16384
	ds_read_b128 v[140:143], v148 offset:17408
	ds_read_b128 v[144:147], v148 offset:18432
	ds_read_b128 v[148:151], v148 offset:19456
	ds_read_b128 v[152:155], v168
	ds_read_b128 v[156:159], v168 offset:1024
	ds_read_b128 v[160:163], v168 offset:2048
	ds_read_b128 v[164:167], v168 offset:3072
	s_setprio 1
	s_waitcnt lgkmcnt(3)
	v_mfma_f32_16x16x32_bf16 v[124:127], v[152:155], v[136:139], v[124:127]
	v_mfma_f32_16x16x32_bf16 v[120:123], v[152:155], v[140:143], v[120:123]
	v_mfma_f32_16x16x32_bf16 v[116:119], v[152:155], v[144:147], v[116:119]
	v_mfma_f32_16x16x32_bf16 v[112:115], v[152:155], v[148:151], v[112:115]
	s_waitcnt lgkmcnt(2)
	v_mfma_f32_16x16x32_bf16 v[108:111], v[156:159], v[136:139], v[108:111]
	v_mfma_f32_16x16x32_bf16 v[96:99], v[156:159], v[140:143], v[96:99]
	v_mfma_f32_16x16x32_bf16 v[84:87], v[156:159], v[144:147], v[84:87]
	v_mfma_f32_16x16x32_bf16 v[80:83], v[156:159], v[148:151], v[80:83]
	s_waitcnt lgkmcnt(1)
	v_mfma_f32_16x16x32_bf16 v[76:79], v[160:163], v[136:139], v[76:79]
	v_mfma_f32_16x16x32_bf16 v[72:75], v[160:163], v[140:143], v[72:75]
	v_mfma_f32_16x16x32_bf16 v[68:71], v[160:163], v[144:147], v[68:71]
	v_mfma_f32_16x16x32_bf16 v[64:67], v[160:163], v[148:151], v[64:67]
	s_waitcnt lgkmcnt(0)
	v_mfma_f32_16x16x32_bf16 v[60:63], v[164:167], v[136:139], v[60:63]
	v_mfma_f32_16x16x32_bf16 v[56:59], v[164:167], v[140:143], v[56:59]
	v_mfma_f32_16x16x32_bf16 v[52:55], v[164:167], v[144:147], v[52:55]
	v_mfma_f32_16x16x32_bf16 v[48:51], v[164:167], v[148:151], v[48:51]
	s_setprio 0
	ds_read_b128 v[152:155], v168 offset:4096
	ds_read_b128 v[156:159], v168 offset:5120
	ds_read_b128 v[160:163], v168 offset:6144
	ds_read_b128 v[164:167], v168 offset:7168
	s_setprio 1
	s_waitcnt lgkmcnt(3)
	v_mfma_f32_16x16x32_bf16 v[44:47], v[152:155], v[136:139], v[44:47]
	v_mfma_f32_16x16x32_bf16 v[40:43], v[152:155], v[140:143], v[40:43]
	v_mfma_f32_16x16x32_bf16 v[36:39], v[152:155], v[144:147], v[36:39]
	v_mfma_f32_16x16x32_bf16 v[32:35], v[152:155], v[148:151], v[32:35]
	s_waitcnt lgkmcnt(2)
	v_mfma_f32_16x16x32_bf16 v[28:31], v[156:159], v[136:139], v[28:31]
	v_mfma_f32_16x16x32_bf16 v[24:27], v[156:159], v[140:143], v[24:27]
	v_mfma_f32_16x16x32_bf16 v[20:23], v[156:159], v[144:147], v[20:23]
	v_mfma_f32_16x16x32_bf16 v[16:19], v[156:159], v[148:151], v[16:19]
	s_waitcnt lgkmcnt(1)
	v_mfma_f32_16x16x32_bf16 v[12:15], v[160:163], v[136:139], v[12:15]
	v_mfma_f32_16x16x32_bf16 v[8:11], v[160:163], v[140:143], v[8:11]
	v_mfma_f32_16x16x32_bf16 v[4:7], v[160:163], v[144:147], v[4:7]
	v_mfma_f32_16x16x32_bf16 v[0:3], v[160:163], v[148:151], v[0:3]
	s_waitcnt lgkmcnt(0)
	v_mfma_f32_16x16x32_bf16 v[136:139], v[164:167], v[136:139], v[88:91]
	v_mfma_f32_16x16x32_bf16 v[140:143], v[164:167], v[140:143], v[92:95]
	v_mfma_f32_16x16x32_bf16 v[144:147], v[164:167], v[144:147], v[100:103]
	v_mfma_f32_16x16x32_bf16 v[148:151], v[164:167], v[148:151], v[104:107]
	s_setprio 0
	s_add_i32 s2, s43, 1
	s_cmp_lg_u32 s43, 2
	s_cselect_b32 s2, s2, 0
	s_mul_i32 s3, s2, 0x6000
	v_add_u32_e32 v100, s3, v134
	v_add_u32_e32 v134, v100, v135
	v_add_u32_e32 v100, v100, v128
	s_waitcnt vmcnt(0)
	s_barrier
	ds_read_b128 v[152:155], v134 offset:3072
	ds_read_b128 v[156:159], v134 offset:2048
	ds_read_b128 v[88:91], v134 offset:1024
	ds_read_b128 v[92:95], v134
	ds_read_b128 v[160:163], v100 offset:19456
	ds_read_b128 v[164:167], v100 offset:18432
	ds_read_b128 v[168:171], v100 offset:17408
	ds_read_b128 v[184:187], v100 offset:16384
	s_setprio 1
	s_waitcnt lgkmcnt(0)
	v_mfma_f32_16x16x32_bf16 v[124:127], v[92:95], v[184:187], v[124:127]
	v_mfma_f32_16x16x32_bf16 v[120:123], v[92:95], v[168:171], v[120:123]
	v_mfma_f32_16x16x32_bf16 v[116:119], v[92:95], v[164:167], v[116:119]
	v_mfma_f32_16x16x32_bf16 v[112:115], v[92:95], v[160:163], v[112:115]
	v_mfma_f32_16x16x32_bf16 v[108:111], v[88:91], v[184:187], v[108:111]
	v_mfma_f32_16x16x32_bf16 v[104:107], v[88:91], v[168:171], v[96:99]
	v_mfma_f32_16x16x32_bf16 v[100:103], v[88:91], v[164:167], v[84:87]
	v_mfma_f32_16x16x32_bf16 v[96:99], v[88:91], v[160:163], v[80:83]
	v_mfma_f32_16x16x32_bf16 v[92:95], v[156:159], v[184:187], v[76:79]
	v_mfma_f32_16x16x32_bf16 v[88:91], v[156:159], v[168:171], v[72:75]
	v_mfma_f32_16x16x32_bf16 v[84:87], v[156:159], v[164:167], v[68:71]
	v_mfma_f32_16x16x32_bf16 v[80:83], v[156:159], v[160:163], v[64:67]
	v_mfma_f32_16x16x32_bf16 v[76:79], v[152:155], v[184:187], v[60:63]
	v_mfma_f32_16x16x32_bf16 v[72:75], v[152:155], v[168:171], v[56:59]
	v_mfma_f32_16x16x32_bf16 v[68:71], v[152:155], v[164:167], v[52:55]
	v_mfma_f32_16x16x32_bf16 v[64:67], v[152:155], v[160:163], v[48:51]
	s_setprio 0
	s_nop 1
	ds_read_b128 v[48:51], v134 offset:4096
	ds_read_b128 v[152:155], v134 offset:5120
	ds_read_b128 v[156:159], v134 offset:6144
	ds_read_b128 v[188:191], v134 offset:7168
	s_setprio 1
	s_waitcnt lgkmcnt(3)
	v_mfma_f32_16x16x32_bf16 v[60:63], v[48:51], v[184:187], v[44:47]
	v_mfma_f32_16x16x32_bf16 v[56:59], v[48:51], v[168:171], v[40:43]
	v_mfma_f32_16x16x32_bf16 v[52:55], v[48:51], v[164:167], v[36:39]
	v_mfma_f32_16x16x32_bf16 v[48:51], v[48:51], v[160:163], v[32:35]
	s_waitcnt lgkmcnt(2)
	v_mfma_f32_16x16x32_bf16 v[44:47], v[152:155], v[184:187], v[28:31]
	v_mfma_f32_16x16x32_bf16 v[40:43], v[152:155], v[168:171], v[24:27]
	v_mfma_f32_16x16x32_bf16 v[36:39], v[152:155], v[164:167], v[20:23]
	v_mfma_f32_16x16x32_bf16 v[32:35], v[152:155], v[160:163], v[16:19]
	s_waitcnt lgkmcnt(1)
	v_mfma_f32_16x16x32_bf16 v[28:31], v[156:159], v[184:187], v[12:15]
	v_mfma_f32_16x16x32_bf16 v[24:27], v[156:159], v[168:171], v[8:11]
	v_mfma_f32_16x16x32_bf16 v[20:23], v[156:159], v[164:167], v[4:7]
	v_mfma_f32_16x16x32_bf16 v[16:19], v[156:159], v[160:163], v[0:3]
	s_waitcnt lgkmcnt(0)
	v_mfma_f32_16x16x32_bf16 v[12:15], v[188:191], v[184:187], v[136:139]
	v_mfma_f32_16x16x32_bf16 v[8:11], v[188:191], v[168:171], v[140:143]
	v_mfma_f32_16x16x32_bf16 v[4:7], v[188:191], v[164:167], v[144:147]
	v_mfma_f32_16x16x32_bf16 v[0:3], v[188:191], v[160:163], v[148:151]
	s_setprio 0
	s_add_i32 s3, s2, 1
	s_cmp_lg_u32 s2, 2
	s_cselect_b32 s50, s3, 0
	s_and_b64 vcc, exec, s[30:31]
	s_cbranch_vccz .LBB0_284
; DEVI int opaque_tid() { int t = (int)threadIdx.x; asm volatile("" : "+v"(t)); return t; }
; DEVI void g2_issue(const G2Tile& t, int kt, int st, char* smem) {
;     const int tid = opaque_tid(), lane = tid & 63, w = tid >> 6;
;     const int rr = lane >> 2, sch = (lane & 3) ^ ((lane >> 5) << 1);
;     const bf16_t* ap = t.A + (size_t)kt * 32 + (size_t)(w * 16 + rr) * t.lda + sch * 8;
;     const bf16_t* bp = t.Bt + (size_t)kt * 32 + (size_t)(w * 16 + rr) * t.ldb + sch * 8;
;     char* sa = smem + st * 24576 + w * 1024 + lane * 16;
; #pragma unroll
;     for (int i = 0; i < 4; ++i) __builtin_amdgcn_global_load_lds((const unsigned*)(ap + (size_t)(64 * i) * t.lda), (unsigned*)(sa + i * 4096), 16, 0, 0);
; #pragma unroll
;     for (int i = 0; i < 2; ++i) __builtin_amdgcn_global_load_lds((const unsigned*)(bp + (size_t)(64 * i) * t.ldb), (unsigned*)(sa + 16384 + i * 4096), 16, 0, 0);
; }
; DEVI void g2_prologue(const G2Tile& t, int st, char* smem) {
;     g2_issue(t, 0, st, smem);
;     g2_issue(t, 1, st == 2 ? 0 : st + 1, smem);
; }
	v_mov_b32_e32 v128, v172
	s_mul_i32 s2, s50, 0x6000
	v_ashrrev_i32_e32 v139, 6, v128
	v_bfe_u32 v134, v128, 2, 4
	v_and_b32_e32 v138, 63, v128
	v_and_b32_e32 v135, 3, v128
	v_lshrrev_b32_e32 v128, 4, v128
	v_lshl_or_b32 v134, v139, 4, v134
	v_bitop3_b32 v128, v128, v135, 2 bitop3:0x6c
	v_ashrrev_i32_e32 v135, 31, v134
	s_add_i32 s3, s2, 0
	v_lshlrev_b32_e32 v139, 10, v139
	v_lshlrev_b32_e32 v138, 4, v138
	v_lshlrev_b64 v[134:135], 11, v[134:135]
	v_add3_u32 v140, s3, v139, v138
	v_lshl_add_u64 v[136:137], s[0:1], 0, v[134:135]
	v_lshlrev_b32_e32 v128, 4, v128
	v_readfirstlane_b32 s3, v140
	v_add_u32_e32 v141, 0x1000, v140
	v_lshl_add_u64 v[136:137], v[136:137], 0, v[128:129]
	s_mov_b32 m0, s3
	v_readfirstlane_b32 s3, v141
	v_add_u32_e32 v141, 0x2000, v140
	global_load_lds_dwordx4 v[136:137], off
	v_lshl_add_u64 v[138:139], v[136:137], 0, s[22:23]
	s_mov_b32 m0, s3
	v_readfirstlane_b32 s3, v141
	global_load_lds_dwordx4 v[138:139], off
	v_lshl_add_u64 v[138:139], v[136:137], 0, s[24:25]
	s_mov_b32 m0, s3
	v_lshl_add_u64 v[134:135], s[20:21], 0, v[134:135]
	global_load_lds_dwordx4 v[138:139], off
	v_add_u32_e32 v138, 0x3000, v140
	v_lshl_add_u64 v[134:135], v[134:135], 0, v[128:129]
	v_readfirstlane_b32 s3, v138
	v_add_u32_e32 v128, 0x4000, v140
	v_lshl_add_u64 v[136:137], v[136:137], 0, s[28:29]
	s_mov_b32 m0, s3
	v_readfirstlane_b32 s3, v128
	v_add_u32_e32 v128, 0x5000, v140
	global_load_lds_dwordx4 v[136:137], off
	s_mov_b32 m0, s3
	v_readfirstlane_b32 s3, v128
	global_load_lds_dwordx4 v[134:135], off
	v_lshl_add_u64 v[134:135], v[134:135], 0, s[22:23]
	s_mov_b32 m0, s3
	v_mov_b32_e32 v128, v172
	global_load_lds_dwordx4 v[134:135], off
	s_addk_i32 s2, 0x6000
	v_ashrrev_i32_e32 v141, 6, v128
	v_bfe_u32 v134, v128, 2, 4
	v_and_b32_e32 v140, 63, v128
	v_and_b32_e32 v135, 3, v128
	v_lshrrev_b32_e32 v128, 4, v128
	v_lshl_or_b32 v134, v141, 4, v134
	s_cmp_lg_u32 s50, 2
	v_bitop3_b32 v128, v128, v135, 2 bitop3:0x6c
	v_ashrrev_i32_e32 v135, 31, v134
	s_cselect_b32 s2, s2, 0
	v_lshlrev_b64 v[134:135], 11, v[134:135]
	s_add_i32 s2, s2, 0
	v_lshlrev_b32_e32 v141, 10, v141
	v_lshlrev_b32_e32 v140, 4, v140
	v_lshl_add_u64 v[136:137], s[0:1], 0, v[134:135]
	v_lshlrev_b32_e32 v128, 4, v128
	v_add3_u32 v140, s2, v141, v140
	v_lshl_add_u64 v[136:137], v[136:137], 0, v[128:129]
	v_readfirstlane_b32 s2, v140
	v_add_u32_e32 v141, 0x1000, v140
	v_lshl_add_u64 v[138:139], v[136:137], 0, 64
	s_mov_b32 m0, s2
	v_readfirstlane_b32 s2, v141
	v_add_u32_e32 v141, 0x2000, v140
	global_load_lds_dwordx4 v[138:139], off
	v_lshl_add_u64 v[138:139], v[136:137], 0, s[58:59]
	s_mov_b32 m0, s2
	v_readfirstlane_b32 s2, v141
	global_load_lds_dwordx4 v[138:139], off
	v_lshl_add_u64 v[138:139], v[136:137], 0, s[60:61]
	s_mov_b32 m0, s2
	v_lshl_add_u64 v[134:135], s[20:21], 0, v[134:135]
	global_load_lds_dwordx4 v[138:139], off
	v_add_u32_e32 v138, 0x3000, v140
	v_lshl_add_u64 v[134:135], v[134:135], 0, v[128:129]
	v_readfirstlane_b32 s2, v138
	v_add_u32_e32 v128, 0x4000, v140
	v_lshl_add_u64 v[136:137], v[136:137], 0, s[62:63]
	s_mov_b32 m0, s2
	v_readfirstlane_b32 s2, v128
	v_add_u32_e32 v128, 0x5000, v140
	global_load_lds_dwordx4 v[136:137], off
	v_lshl_add_u64 v[136:137], v[134:135], 0, 64
	s_mov_b32 m0, s2
	v_readfirstlane_b32 s2, v128
	global_load_lds_dwordx4 v[136:137], off
	v_lshl_add_u64 v[134:135], v[134:135], 0, s[58:59]
	s_mov_b32 m0, s2
	s_nop 0
	global_load_lds_dwordx4 v[134:135], off

; DEVI int opaque_tid() { int t = (int)threadIdx.x; asm volatile("" : "+v"(t)); return t; }
; DEVI void g2_issue(const G2Tile& t, int kt, int st, char* smem) {
;     const int tid = opaque_tid(), lane = tid & 63, w = tid >> 6;
;     const int rr = lane >> 2, sch = (lane & 3) ^ ((lane >> 5) << 1);
;     const bf16_t* ap = t.A + (size_t)kt * 32 + (size_t)(w * 16 + rr) * t.lda + sch * 8;
;     const bf16_t* bp = t.Bt + (size_t)kt * 32 + (size_t)(w * 16 + rr) * t.ldb + sch * 8;
;     char* sa = smem + st * 24576 + w * 1024 + lane * 16;
; #pragma unroll
;     for (int i = 0; i < 4; ++i) __builtin_amdgcn_global_load_lds((const unsigned*)(ap + (size_t)(64 * i) * t.lda), (unsigned*)(sa + i * 4096), 16, 0, 0);
; #pragma unroll
;     for (int i = 0; i < 2; ++i) __builtin_amdgcn_global_load_lds((const unsigned*)(bp + (size_t)(64 * i) * t.ldb), (unsigned*)(sa + 16384 + i * 4096), 16, 0, 0);
; }
; DEVI void g2_prologue(const G2Tile& t, int st, char* smem) {
;     g2_issue(t, 0, st, smem);
;     g2_issue(t, 1, st == 2 ? 0 : st + 1, smem);
; }
; template <bool TRANS, class Epi>
; DEVI int g2_body(const G2Tile& t, int st, char* smem, bool has_next, const G2Tile& nxt, const Epi& epi) {
;     const int tid = opaque_tid(), lane = tid & 63, w = tid >> 6, wr = w >> 1, wc = w & 1, fr = lane & 15, fq = lane >> 4;
;     f32x4 acc[8][4];
; #pragma unroll
;     for (int m = 0; m < 8; ++m)
; #pragma unroll
;         for (int n = 0; n < 4; ++n) acc[m][n] = (f32x4){0.f, 0.f, 0.f, 0.f};
;     const int frag = fr * 64 + ((fq ^ ((fr >> 3) << 1)) << 4);
;     const int nk = t.nk;
.LBB0_1502:
	v_mov_b32_e32 v130, v172
	s_mov_b64 s[36:37], 0
	v_lshrrev_b32_e32 v2, 2, v130
	v_lshrrev_b32_e32 v134, 4, v130
	v_and_b32_e32 v2, 2, v2
	v_lshlrev_b32_e32 v0, 6, v130
	v_bitop3_b32 v2, v134, v2, 3 bitop3:0x6c
	v_bfe_u32 v131, v130, 6, 1
	v_and_b32_e32 v1, 0x3c0, v0
	v_lshlrev_b32_e32 v2, 4, v2
	v_and_b32_e32 v133, 0xffffe000, v0
	v_mov_b32_e32 v0, 0
	v_bfe_u32 v135, v130, 4, 2
	v_add3_u32 v132, 0, v1, v2
	v_lshlrev_b32_e32 v128, 12, v131
	v_mov_b32_e32 v1, v0
	v_mov_b32_e32 v2, v0
	v_mov_b32_e32 v3, v0
	v_mov_b32_e32 v4, v0
	v_mov_b32_e32 v5, v0
	v_mov_b32_e32 v6, v0
	v_mov_b32_e32 v7, v0
	v_mov_b32_e32 v8, v0
	v_mov_b32_e32 v9, v0
	v_mov_b32_e32 v10, v0
	v_mov_b32_e32 v11, v0
	v_mov_b32_e32 v12, v0
	v_mov_b32_e32 v13, v0
	v_mov_b32_e32 v14, v0
	v_mov_b32_e32 v15, v0
	v_mov_b32_e32 v16, v0
	v_mov_b32_e32 v17, v0
	v_mov_b32_e32 v18, v0
	v_mov_b32_e32 v19, v0
	v_mov_b32_e32 v20, v0
	v_mov_b32_e32 v21, v0
	v_mov_b32_e32 v22, v0
	v_mov_b32_e32 v23, v0
	v_mov_b32_e32 v24, v0
	v_mov_b32_e32 v25, v0
	v_mov_b32_e32 v26, v0
	v_mov_b32_e32 v27, v0
	v_mov_b32_e32 v28, v0
	v_mov_b32_e32 v29, v0
	v_mov_b32_e32 v30, v0
	v_mov_b32_e32 v31, v0
	v_mov_b32_e32 v32, v0
	v_mov_b32_e32 v33, v0
	v_mov_b32_e32 v34, v0
	v_mov_b32_e32 v35, v0
	v_mov_b32_e32 v36, v0
	v_mov_b32_e32 v37, v0
	v_mov_b32_e32 v38, v0
	v_mov_b32_e32 v39, v0
	v_mov_b32_e32 v40, v0
	v_mov_b32_e32 v41, v0
	v_mov_b32_e32 v42, v0
	v_mov_b32_e32 v43, v0
	v_mov_b32_e32 v44, v0
	v_mov_b32_e32 v45, v0
	v_mov_b32_e32 v46, v0
	v_mov_b32_e32 v47, v0
	v_mov_b32_e32 v48, v0
	v_mov_b32_e32 v49, v0
	v_mov_b32_e32 v50, v0
	v_mov_b32_e32 v51, v0
	v_mov_b32_e32 v52, v0
	v_mov_b32_e32 v53, v0
	v_mov_b32_e32 v54, v0
	v_mov_b32_e32 v55, v0
	v_mov_b32_e32 v56, v0
	v_mov_b32_e32 v57, v0
	v_mov_b32_e32 v58, v0
	v_mov_b32_e32 v59, v0
	v_mov_b32_e32 v60, v0
	v_mov_b32_e32 v61, v0
	v_mov_b32_e32 v62, v0
	v_mov_b32_e32 v63, v0
	v_mov_b32_e32 v64, v0
	v_mov_b32_e32 v65, v0
	v_mov_b32_e32 v66, v0
	v_mov_b32_e32 v67, v0
	v_mov_b32_e32 v68, v0
	v_mov_b32_e32 v69, v0
	v_mov_b32_e32 v70, v0
	v_mov_b32_e32 v71, v0
	v_mov_b32_e32 v72, v0
	v_mov_b32_e32 v73, v0
	v_mov_b32_e32 v74, v0
	v_mov_b32_e32 v75, v0
	v_mov_b32_e32 v76, v0
	v_mov_b32_e32 v77, v0
	v_mov_b32_e32 v78, v0
	v_mov_b32_e32 v79, v0
	v_mov_b32_e32 v80, v0
	v_mov_b32_e32 v81, v0
	v_mov_b32_e32 v82, v0
	v_mov_b32_e32 v83, v0
	v_mov_b32_e32 v84, v0
	v_mov_b32_e32 v85, v0
	v_mov_b32_e32 v86, v0
	v_mov_b32_e32 v87, v0
	v_mov_b32_e32 v96, v0
	v_mov_b32_e32 v97, v0
	v_mov_b32_e32 v98, v0
	v_mov_b32_e32 v99, v0
	v_mov_b32_e32 v108, v0
	v_mov_b32_e32 v109, v0
	v_mov_b32_e32 v110, v0
	v_mov_b32_e32 v111, v0
	v_mov_b32_e32 v112, v0
	v_mov_b32_e32 v113, v0
	v_mov_b32_e32 v114, v0
	v_mov_b32_e32 v115, v0
	v_mov_b32_e32 v116, v0
	v_mov_b32_e32 v117, v0
	v_mov_b32_e32 v118, v0
	v_mov_b32_e32 v119, v0
	v_mov_b32_e32 v120, v0
	v_mov_b32_e32 v121, v0
	v_mov_b32_e32 v122, v0
	v_mov_b32_e32 v123, v0
	v_mov_b32_e32 v124, v0
	v_mov_b32_e32 v125, v0
	v_mov_b32_e32 v126, v0
	v_mov_b32_e32 v127, v0
	v_mov_b32_e32 v88, v0
	v_mov_b32_e32 v89, v0
	v_mov_b32_e32 v90, v0
	v_mov_b32_e32 v91, v0
	v_mov_b32_e32 v92, v0
	v_mov_b32_e32 v93, v0
	v_mov_b32_e32 v94, v0
	v_mov_b32_e32 v95, v0
	v_mov_b32_e32 v100, v0
	v_mov_b32_e32 v101, v0
	v_mov_b32_e32 v102, v0
	v_mov_b32_e32 v103, v0
	v_mov_b32_e32 v104, v0
	v_mov_b32_e32 v105, v0
	v_mov_b32_e32 v106, v0
	v_mov_b32_e32 v107, v0
	v_and_b32_e32 v224, 3, v172
	v_lshrrev_b32_e32 v225, 4, v172
	v_bitop3_b32 v224, v225, v224, 2 bitop3:0x6c
	v_ashrrev_i32_e32 v225, 6, v172
	v_bfe_u32 v222, v172, 2, 4
	v_readfirstlane_b32 s32, v225
	v_lshl_or_b32 v222, v225, 4, v222
	v_lshlrev_b32_e32 v222, 11, v222
	v_lshl_or_b32 v222, v224, 4, v222
	v_mov_b32_e32 v223, 0
	s_lshl_b32 s32, s32, 10
	v_lshl_add_u64 v[208:209], s[28:29], 0, v[222:223]
	v_lshl_add_u64 v[208:209], v[208:209], 0, s[12:13]
	v_lshl_add_u64 v[210:211], s[28:29], 0, v[222:223]
	v_lshl_add_u64 v[210:211], v[210:211], 0, s[14:15]
	v_lshl_add_u64 v[212:213], s[28:29], 0, v[222:223]
	v_lshl_add_u64 v[212:213], v[212:213], 0, s[16:17]
	v_lshl_add_u64 v[214:215], s[28:29], 0, v[222:223]
	v_lshl_add_u64 v[214:215], v[214:215], 0, s[18:19]
	v_lshl_add_u64 v[218:219], s[30:31], 0, v[222:223]
	v_lshl_add_u64 v[218:219], v[218:219], 0, s[12:13]
	v_lshl_add_u64 v[220:221], s[30:31], 0, v[222:223]
	v_lshl_add_u64 v[220:221], v[220:221], 0, s[14:15]
; template <bool TRANS, class Epi>
; DEVI int g2_body(const G2Tile& t, int st, char* smem, bool has_next, const G2Tile& nxt, const Epi& epi) {
;     ...
;     for (int kt = 0; kt < nk; ++kt) {
;         if (kt + 1 < nk) asm volatile("s_waitcnt vmcnt(6)" ::: "memory");
;         else asm volatile("s_waitcnt vmcnt(0)" ::: "memory");
;         __syncthreads();
;         if (kt + 2 < nk) g2_issue(t, kt + 2, st >= 1 ? st - 1 : 2, smem);
;         const char* sa = smem + st * 24576 + frag;
;         bf16x8 bfr[4];
; #pragma unroll
;         for (int n = 0; n < 4; ++n) bfr[n] = *(const bf16x8*)(sa + (16 + wc * 4 + n) * 1024);
; #pragma unroll
;         for (int mh = 0; mh < 2; ++mh) {
;             bf16x8 af[4];
; #pragma unroll
;             for (int m = 0; m < 4; ++m) af[m] = *(const bf16x8*)(sa + (wr * 8 + mh * 4 + m) * 1024);
;             __builtin_amdgcn_s_setprio(1);
; #pragma unroll
;             for (int m = 0; m < 4; ++m)
; #pragma unroll
;                 for (int n = 0; n < 4; ++n)
;                     acc[mh * 4 + m][n] = TRANS ? __builtin_amdgcn_mfma_f32_16x16x32_bf16(bfr[n], af[m], acc[mh * 4 + m][n], 0, 0, 0)
;                                                : __builtin_amdgcn_mfma_f32_16x16x32_bf16(af[m], bfr[n], acc[mh * 4 + m][n], 0, 0, 0);
;             __builtin_amdgcn_s_setprio(0);
;         }
;         st = st == 2 ? 0 : st + 1;
;     }
.LBB0_1503:
	s_waitcnt vmcnt(6)
	s_waitcnt lgkmcnt(0)
	s_barrier
	s_mul_i32 s26, s43, 0x6000
	s_add_i32 s33, s26, 0xffffa000
	s_cmp_gt_i32 s43, 0
	s_cselect_b32 s33, s33, 0xc000
	s_add_i32 s33, s33, s32
	v_add_u32_e32 v152, s26, v132
	v_add_u32_e32 v148, v152, v128
	v_add_u32_e32 v168, v152, v133
	ds_read_b128 v[136:139], v148 offset:16384
	ds_read_b128 v[140:143], v148 offset:17408
	ds_read_b128 v[144:147], v148 offset:18432
	ds_read_b128 v[148:151], v148 offset:19456
	ds_read_b128 v[152:155], v168
	ds_read_b128 v[156:159], v168 offset:1024
	ds_read_b128 v[160:163], v168 offset:2048
	ds_read_b128 v[164:167], v168 offset:3072
	ds_read_b128 v[192:195], v168 offset:4096
	ds_read_b128 v[196:199], v168 offset:5120
	ds_read_b128 v[200:203], v168 offset:6144
	ds_read_b128 v[204:207], v168 offset:7168
	s_mov_b32 m0, s33
	s_nop 0
	global_load_lds_dwordx4 v[208:209], off
	v_lshl_add_u64 v[208:209], v[208:209], 0, 64
	s_add_i32 m0, s33, 0x1000
	s_setprio 1
	s_waitcnt lgkmcnt(7)
	v_mfma_f32_16x16x32_bf16 v[124:127], v[136:139], v[152:155], v[124:127]
	v_mfma_f32_16x16x32_bf16 v[120:123], v[140:143], v[152:155], v[120:123]
	v_mfma_f32_16x16x32_bf16 v[116:119], v[144:147], v[152:155], v[116:119]
	v_mfma_f32_16x16x32_bf16 v[112:115], v[148:151], v[152:155], v[112:115]
	global_load_lds_dwordx4 v[210:211], off
	v_lshl_add_u64 v[210:211], v[210:211], 0, 64
	s_add_i32 m0, s33, 0x2000
	s_waitcnt lgkmcnt(6)
	v_mfma_f32_16x16x32_bf16 v[108:111], v[136:139], v[156:159], v[108:111]
	v_mfma_f32_16x16x32_bf16 v[96:99], v[140:143], v[156:159], v[96:99]
	v_mfma_f32_16x16x32_bf16 v[84:87], v[144:147], v[156:159], v[84:87]
	v_mfma_f32_16x16x32_bf16 v[80:83], v[148:151], v[156:159], v[80:83]
	global_load_lds_dwordx4 v[212:213], off
	v_lshl_add_u64 v[212:213], v[212:213], 0, 64
	s_add_i32 m0, s33, 0x3000
	s_waitcnt lgkmcnt(5)
	v_mfma_f32_16x16x32_bf16 v[76:79], v[136:139], v[160:163], v[76:79]
	v_mfma_f32_16x16x32_bf16 v[72:75], v[140:143], v[160:163], v[72:75]
	v_mfma_f32_16x16x32_bf16 v[68:71], v[144:147], v[160:163], v[68:71]
	v_mfma_f32_16x16x32_bf16 v[64:67], v[148:151], v[160:163], v[64:67]
	global_load_lds_dwordx4 v[214:215], off
	v_lshl_add_u64 v[214:215], v[214:215], 0, 64
	s_add_i32 m0, s33, 0x4000
	s_waitcnt lgkmcnt(4)
	v_mfma_f32_16x16x32_bf16 v[60:63], v[136:139], v[164:167], v[60:63]
	v_mfma_f32_16x16x32_bf16 v[56:59], v[140:143], v[164:167], v[56:59]
	v_mfma_f32_16x16x32_bf16 v[52:55], v[144:147], v[164:167], v[52:55]
	v_mfma_f32_16x16x32_bf16 v[48:51], v[148:151], v[164:167], v[48:51]
	global_load_lds_dwordx4 v[218:219], off
	v_lshl_add_u64 v[218:219], v[218:219], 0, 64
	s_add_i32 m0, s33, 0x5000
	s_waitcnt lgkmcnt(3)
	v_mfma_f32_16x16x32_bf16 v[44:47], v[136:139], v[192:195], v[44:47]
	v_mfma_f32_16x16x32_bf16 v[40:43], v[140:143], v[192:195], v[40:43]
	v_mfma_f32_16x16x32_bf16 v[36:39], v[144:147], v[192:195], v[36:39]
	v_mfma_f32_16x16x32_bf16 v[32:35], v[148:151], v[192:195], v[32:35]
	global_load_lds_dwordx4 v[220:221], off
	v_lshl_add_u64 v[220:221], v[220:221], 0, 64
	s_waitcnt lgkmcnt(2)
	v_mfma_f32_16x16x32_bf16 v[28:31], v[136:139], v[196:199], v[28:31]
	v_mfma_f32_16x16x32_bf16 v[24:27], v[140:143], v[196:199], v[24:27]
	v_mfma_f32_16x16x32_bf16 v[20:23], v[144:147], v[196:199], v[20:23]
	v_mfma_f32_16x16x32_bf16 v[16:19], v[148:151], v[196:199], v[16:19]
	s_waitcnt lgkmcnt(1)
	v_mfma_f32_16x16x32_bf16 v[12:15], v[136:139], v[200:203], v[12:15]
	v_mfma_f32_16x16x32_bf16 v[8:11], v[140:143], v[200:203], v[8:11]
	v_mfma_f32_16x16x32_bf16 v[4:7], v[144:147], v[200:203], v[4:7]
	v_mfma_f32_16x16x32_bf16 v[0:3], v[148:151], v[200:203], v[0:3]
	s_waitcnt lgkmcnt(0)
	v_mfma_f32_16x16x32_bf16 v[88:91], v[136:139], v[204:207], v[88:91]
	v_mfma_f32_16x16x32_bf16 v[92:95], v[140:143], v[204:207], v[92:95]
	v_mfma_f32_16x16x32_bf16 v[100:103], v[144:147], v[204:207], v[100:103]
	v_mfma_f32_16x16x32_bf16 v[104:107], v[148:151], v[204:207], v[104:107]
	s_setprio 0
	s_add_i32 s26, s43, 1
	s_cmp_lg_u32 s43, 2
	s_cselect_b32 s43, s26, 0
	s_add_u32 s36, s36, 64
	s_addc_u32 s37, s37, 0
	s_cmpk_eq_i32 s36, 0x780
	s_cbranch_scc0 .LBB0_1503
	s_mul_i32 s26, s43, 0x6000
	v_add_u32_e32 v152, s26, v132
	v_add_u32_e32 v148, v152, v128
	v_add_u32_e32 v168, v152, v133
	s_waitcnt vmcnt(6)
	s_waitcnt vmcnt(0)
	s_barrier
; template <bool TRANS, class Epi>
; DEVI int g2_body(const G2Tile& t, int st, char* smem, bool has_next, const G2Tile& nxt, const Epi& epi) {
;     ...
;     for (int kt = 0; kt < nk; ++kt) {
;         if (kt + 1 < nk) asm volatile("s_waitcnt vmcnt(6)" ::: "memory");
;         else asm volatile("s_waitcnt vmcnt(0)" ::: "memory");
;         __syncthreads();
;         if (kt + 2 < nk) g2_issue(t, kt + 2, st >= 1 ? st - 1 : 2, smem);
;         const char* sa = smem + st * 24576 + frag;
;         bf16x8 bfr[4];
; #pragma unroll
;         for (int n = 0; n < 4; ++n) bfr[n] = *(const bf16x8*)(sa + (16 + wc * 4 + n) * 1024);
; #pragma unroll
;         for (int mh = 0; mh < 2; ++mh) {
;             bf16x8 af[4];
; #pragma unroll
;             for (int m = 0; m < 4; ++m) af[m] = *(const bf16x8*)(sa + (wr * 8 + mh * 4 + m) * 1024);
;             __builtin_amdgcn_s_setprio(1);
; #pragma unroll
;             for (int m = 0; m < 4; ++m)
; #pragma unroll
;                 for (int n = 0; n < 4; ++n)
;                     acc[mh * 4 + m][n] = TRANS ? __builtin_amdgcn_mfma_f32_16x16x32_bf16(bfr[n], af[m], acc[mh * 4 + m][n], 0, 0, 0)
;                                                : __builtin_amdgcn_mfma_f32_16x16x32_bf16(af[m], bfr[n], acc[mh * 4 + m][n], 0, 0, 0);
;             __builtin_amdgcn_s_setprio(0);
;         }
;         st = st == 2 ? 0 : st + 1;
;     }
;     if (has_next) g2_prologue(nxt, st, smem);
	ds_read_b128 v[136:139], v148 offset:16384
	ds_read_b128 v[140:143], v148 offset:17408
	ds_read_b128 v[144:147], v148 offset:18432
	ds_read_b128 v[148:151], v148 offset:19456
	ds_read_b128 v[152:155], v168
	ds_read_b128 v[156:159], v168 offset:1024
	ds_read_b128 v[160:163], v168 offset:2048
	ds_read_b128 v[164:167], v168 offset:3072
	s_setprio 1
	s_waitcnt lgkmcnt(3)
	v_mfma_f32_16x16x32_bf16 v[124:127], v[136:139], v[152:155], v[124:127]
	v_mfma_f32_16x16x32_bf16 v[120:123], v[140:143], v[152:155], v[120:123]
	v_mfma_f32_16x16x32_bf16 v[116:119], v[144:147], v[152:155], v[116:119]
	v_mfma_f32_16x16x32_bf16 v[112:115], v[148:151], v[152:155], v[112:115]
	s_waitcnt lgkmcnt(2)
	v_mfma_f32_16x16x32_bf16 v[108:111], v[136:139], v[156:159], v[108:111]
	v_mfma_f32_16x16x32_bf16 v[96:99], v[140:143], v[156:159], v[96:99]
	v_mfma_f32_16x16x32_bf16 v[84:87], v[144:147], v[156:159], v[84:87]
	v_mfma_f32_16x16x32_bf16 v[80:83], v[148:151], v[156:159], v[80:83]
	s_waitcnt lgkmcnt(1)
	v_mfma_f32_16x16x32_bf16 v[76:79], v[136:139], v[160:163], v[76:79]
	v_mfma_f32_16x16x32_bf16 v[72:75], v[140:143], v[160:163], v[72:75]
	v_mfma_f32_16x16x32_bf16 v[68:71], v[144:147], v[160:163], v[68:71]
	v_mfma_f32_16x16x32_bf16 v[64:67], v[148:151], v[160:163], v[64:67]
	s_waitcnt lgkmcnt(0)
	v_mfma_f32_16x16x32_bf16 v[60:63], v[136:139], v[164:167], v[60:63]
	v_mfma_f32_16x16x32_bf16 v[56:59], v[140:143], v[164:167], v[56:59]
	v_mfma_f32_16x16x32_bf16 v[52:55], v[144:147], v[164:167], v[52:55]
	v_mfma_f32_16x16x32_bf16 v[48:51], v[148:151], v[164:167], v[48:51]
	s_setprio 0
	ds_read_b128 v[152:155], v168 offset:4096
	ds_read_b128 v[156:159], v168 offset:5120
	ds_read_b128 v[160:163], v168 offset:6144
	ds_read_b128 v[164:167], v168 offset:7168
	s_setprio 1
	s_waitcnt lgkmcnt(3)
	v_mfma_f32_16x16x32_bf16 v[44:47], v[136:139], v[152:155], v[44:47]
	v_mfma_f32_16x16x32_bf16 v[40:43], v[140:143], v[152:155], v[40:43]
	v_mfma_f32_16x16x32_bf16 v[36:39], v[144:147], v[152:155], v[36:39]
	v_mfma_f32_16x16x32_bf16 v[32:35], v[148:151], v[152:155], v[32:35]
	s_waitcnt lgkmcnt(2)
	v_mfma_f32_16x16x32_bf16 v[28:31], v[136:139], v[156:159], v[28:31]
	v_mfma_f32_16x16x32_bf16 v[24:27], v[140:143], v[156:159], v[24:27]
	v_mfma_f32_16x16x32_bf16 v[20:23], v[144:147], v[156:159], v[20:23]
	v_mfma_f32_16x16x32_bf16 v[16:19], v[148:151], v[156:159], v[16:19]
	s_waitcnt lgkmcnt(1)
	v_mfma_f32_16x16x32_bf16 v[12:15], v[136:139], v[160:163], v[12:15]
	v_mfma_f32_16x16x32_bf16 v[8:11], v[140:143], v[160:163], v[8:11]
	v_mfma_f32_16x16x32_bf16 v[4:7], v[144:147], v[160:163], v[4:7]
	v_mfma_f32_16x16x32_bf16 v[0:3], v[148:151], v[160:163], v[0:3]
	s_waitcnt lgkmcnt(0)
	v_mfma_f32_16x16x32_bf16 v[136:139], v[136:139], v[164:167], v[88:91]
	v_mfma_f32_16x16x32_bf16 v[140:143], v[140:143], v[164:167], v[92:95]
	v_mfma_f32_16x16x32_bf16 v[144:147], v[144:147], v[164:167], v[100:103]
	v_mfma_f32_16x16x32_bf16 v[148:151], v[148:151], v[164:167], v[104:107]
	s_setprio 0
	s_add_i32 s26, s43, 1
	s_cmp_lg_u32 s43, 2
	s_cselect_b32 s26, s26, 0
	s_mul_i32 s28, s26, 0x6000
	v_add_u32_e32 v100, s28, v132
	v_add_u32_e32 v132, v100, v133
	v_add_u32_e32 v100, v100, v128
	s_waitcnt vmcnt(0)
	s_barrier
	ds_read_b128 v[152:155], v132 offset:3072
	ds_read_b128 v[156:159], v132 offset:2048
	ds_read_b128 v[88:91], v132 offset:1024
	ds_read_b128 v[92:95], v132
	ds_read_b128 v[160:163], v100 offset:19456
	ds_read_b128 v[164:167], v100 offset:18432
	ds_read_b128 v[168:171], v100 offset:17408
	ds_read_b128 v[182:185], v100 offset:16384
	s_setprio 1
	s_waitcnt lgkmcnt(0)
	v_mfma_f32_16x16x32_bf16 v[124:127], v[182:185], v[92:95], v[124:127]
	v_mfma_f32_16x16x32_bf16 v[120:123], v[168:171], v[92:95], v[120:123]
	v_mfma_f32_16x16x32_bf16 v[116:119], v[164:167], v[92:95], v[116:119]
	v_mfma_f32_16x16x32_bf16 v[112:115], v[160:163], v[92:95], v[112:115]
	v_mfma_f32_16x16x32_bf16 v[108:111], v[182:185], v[88:91], v[108:111]
	v_mfma_f32_16x16x32_bf16 v[104:107], v[168:171], v[88:91], v[96:99]
	v_mfma_f32_16x16x32_bf16 v[100:103], v[164:167], v[88:91], v[84:87]
	v_mfma_f32_16x16x32_bf16 v[96:99], v[160:163], v[88:91], v[80:83]
	v_mfma_f32_16x16x32_bf16 v[92:95], v[182:185], v[156:159], v[76:79]
	v_mfma_f32_16x16x32_bf16 v[88:91], v[168:171], v[156:159], v[72:75]
	v_mfma_f32_16x16x32_bf16 v[84:87], v[164:167], v[156:159], v[68:71]
	v_mfma_f32_16x16x32_bf16 v[80:83], v[160:163], v[156:159], v[64:67]
	v_mfma_f32_16x16x32_bf16 v[76:79], v[182:185], v[152:155], v[60:63]
	v_mfma_f32_16x16x32_bf16 v[72:75], v[168:171], v[152:155], v[56:59]
	v_mfma_f32_16x16x32_bf16 v[68:71], v[164:167], v[152:155], v[52:55]
	v_mfma_f32_16x16x32_bf16 v[64:67], v[160:163], v[152:155], v[48:51]
	s_setprio 0
	s_nop 1
	ds_read_b128 v[48:51], v132 offset:4096
	ds_read_b128 v[152:155], v132 offset:5120
	ds_read_b128 v[156:159], v132 offset:6144
	ds_read_b128 v[186:189], v132 offset:7168
	s_setprio 1
	s_waitcnt lgkmcnt(3)
	v_mfma_f32_16x16x32_bf16 v[60:63], v[182:185], v[48:51], v[44:47]
	v_mfma_f32_16x16x32_bf16 v[56:59], v[168:171], v[48:51], v[40:43]
	v_mfma_f32_16x16x32_bf16 v[52:55], v[164:167], v[48:51], v[36:39]
	v_mfma_f32_16x16x32_bf16 v[48:51], v[160:163], v[48:51], v[32:35]
	s_waitcnt lgkmcnt(2)
	v_mfma_f32_16x16x32_bf16 v[44:47], v[182:185], v[152:155], v[28:31]
	v_mfma_f32_16x16x32_bf16 v[40:43], v[168:171], v[152:155], v[24:27]
	v_mfma_f32_16x16x32_bf16 v[36:39], v[164:167], v[152:155], v[20:23]
	v_mfma_f32_16x16x32_bf16 v[32:35], v[160:163], v[152:155], v[16:19]
	s_waitcnt lgkmcnt(1)
	v_mfma_f32_16x16x32_bf16 v[28:31], v[182:185], v[156:159], v[12:15]
	v_mfma_f32_16x16x32_bf16 v[24:27], v[168:171], v[156:159], v[8:11]
	v_mfma_f32_16x16x32_bf16 v[20:23], v[164:167], v[156:159], v[4:7]
	v_mfma_f32_16x16x32_bf16 v[16:19], v[160:163], v[156:159], v[0:3]
	s_waitcnt lgkmcnt(0)
	v_mfma_f32_16x16x32_bf16 v[12:15], v[182:185], v[186:189], v[136:139]
	v_mfma_f32_16x16x32_bf16 v[8:11], v[168:171], v[186:189], v[140:143]
	v_mfma_f32_16x16x32_bf16 v[4:7], v[164:167], v[186:189], v[144:147]
	v_mfma_f32_16x16x32_bf16 v[0:3], v[160:163], v[186:189], v[148:151]
	s_setprio 0
	s_add_i32 s28, s26, 1
	s_cmp_lg_u32 s26, 2
	s_cselect_b32 s43, s28, 0
	s_and_b64 vcc, exec, s[34:35]
	s_cbranch_vccz .LBB0_1499
; DEVI int opaque_tid() { int t = (int)threadIdx.x; asm volatile("" : "+v"(t)); return t; }
; DEVI void g2_issue(const G2Tile& t, int kt, int st, char* smem) {
;     const int tid = opaque_tid(), lane = tid & 63, w = tid >> 6;
;     const int rr = lane >> 2, sch = (lane & 3) ^ ((lane >> 5) << 1);
;     const bf16_t* ap = t.A + (size_t)kt * 32 + (size_t)(w * 16 + rr) * t.lda + sch * 8;
;     const bf16_t* bp = t.Bt + (size_t)kt * 32 + (size_t)(w * 16 + rr) * t.ldb + sch * 8;
;     char* sa = smem + st * 24576 + w * 1024 + lane * 16;
; #pragma unroll
;     for (int i = 0; i < 4; ++i) __builtin_amdgcn_global_load_lds((const unsigned*)(ap + (size_t)(64 * i) * t.lda), (unsigned*)(sa + i * 4096), 16, 0, 0);
; #pragma unroll
;     for (int i = 0; i < 2; ++i) __builtin_amdgcn_global_load_lds((const unsigned*)(bp + (size_t)(64 * i) * t.ldb), (unsigned*)(sa + 16384 + i * 4096), 16, 0, 0);
; }
; DEVI void g2_prologue(const G2Tile& t, int st, char* smem) {
;     g2_issue(t, 0, st, smem);
;     g2_issue(t, 1, st == 2 ? 0 : st + 1, smem);
; }
	v_mov_b32_e32 v128, v172
	s_mul_i32 s26, s43, 0x6000
	v_ashrrev_i32_e32 v139, 6, v128
	v_bfe_u32 v132, v128, 2, 4
	v_and_b32_e32 v138, 63, v128
	v_and_b32_e32 v133, 3, v128
	v_lshrrev_b32_e32 v128, 4, v128
	v_lshl_or_b32 v132, v139, 4, v132
	v_bitop3_b32 v128, v128, v133, 2 bitop3:0x6c
	v_ashrrev_i32_e32 v133, 31, v132
	s_add_i32 s28, s26, 0
	v_lshlrev_b32_e32 v139, 10, v139
	v_lshlrev_b32_e32 v138, 4, v138
	v_lshlrev_b64 v[132:133], 11, v[132:133]
	v_add3_u32 v140, s28, v139, v138
	v_lshl_add_u64 v[136:137], s[20:21], 0, v[132:133]
	v_lshlrev_b32_e32 v128, 4, v128
	v_readfirstlane_b32 s28, v140
	v_add_u32_e32 v141, 0x1000, v140
	v_lshl_add_u64 v[136:137], v[136:137], 0, v[128:129]
	s_mov_b32 m0, s28
	v_readfirstlane_b32 s28, v141
	v_add_u32_e32 v141, 0x2000, v140
	global_load_lds_dwordx4 v[136:137], off
	v_lshl_add_u64 v[138:139], v[136:137], 0, s[0:1]
	s_mov_b32 m0, s28
	v_readfirstlane_b32 s28, v141
	global_load_lds_dwordx4 v[138:139], off
	v_lshl_add_u64 v[138:139], v[136:137], 0, s[2:3]
	s_mov_b32 m0, s28
	v_lshl_add_u64 v[132:133], s[22:23], 0, v[132:133]
	global_load_lds_dwordx4 v[138:139], off
	v_add_u32_e32 v138, 0x3000, v140
	v_lshl_add_u64 v[132:133], v[132:133], 0, v[128:129]
	v_readfirstlane_b32 s28, v138
	v_add_u32_e32 v128, 0x4000, v140
	v_lshl_add_u64 v[136:137], v[136:137], 0, s[4:5]
	s_mov_b32 m0, s28
	v_readfirstlane_b32 s28, v128
	v_add_u32_e32 v128, 0x5000, v140
	global_load_lds_dwordx4 v[136:137], off
	s_mov_b32 m0, s28
	v_readfirstlane_b32 s28, v128
	global_load_lds_dwordx4 v[132:133], off
	v_lshl_add_u64 v[132:133], v[132:133], 0, s[0:1]
	s_mov_b32 m0, s28
	v_mov_b32_e32 v128, v172
	global_load_lds_dwordx4 v[132:133], off
	s_addk_i32 s26, 0x6000
	v_ashrrev_i32_e32 v141, 6, v128
	v_bfe_u32 v132, v128, 2, 4
	v_and_b32_e32 v140, 63, v128
	v_and_b32_e32 v133, 3, v128
	v_lshrrev_b32_e32 v128, 4, v128
	v_lshl_or_b32 v132, v141, 4, v132
	s_cmp_lg_u32 s43, 2
	v_bitop3_b32 v128, v128, v133, 2 bitop3:0x6c
	v_ashrrev_i32_e32 v133, 31, v132
	s_cselect_b32 s26, s26, 0
	v_lshlrev_b64 v[132:133], 11, v[132:133]
	s_add_i32 s26, s26, 0
	v_lshlrev_b32_e32 v141, 10, v141
	v_lshlrev_b32_e32 v140, 4, v140
	v_lshl_add_u64 v[136:137], s[20:21], 0, v[132:133]
	v_lshlrev_b32_e32 v128, 4, v128
	v_add3_u32 v140, s26, v141, v140
	v_lshl_add_u64 v[136:137], v[136:137], 0, v[128:129]
	v_readfirstlane_b32 s26, v140
	v_add_u32_e32 v141, 0x1000, v140
	v_lshl_add_u64 v[138:139], v[136:137], 0, 64
	s_mov_b32 m0, s26
	v_readfirstlane_b32 s26, v141
	v_add_u32_e32 v141, 0x2000, v140
	global_load_lds_dwordx4 v[138:139], off
	v_lshl_add_u64 v[138:139], v[136:137], 0, s[6:7]
	s_mov_b32 m0, s26
	v_readfirstlane_b32 s26, v141
	global_load_lds_dwordx4 v[138:139], off
	v_lshl_add_u64 v[138:139], v[136:137], 0, s[8:9]
	s_mov_b32 m0, s26
	v_lshl_add_u64 v[132:133], s[22:23], 0, v[132:133]
	global_load_lds_dwordx4 v[138:139], off
	v_add_u32_e32 v138, 0x3000, v140
	v_lshl_add_u64 v[132:133], v[132:133], 0, v[128:129]
	v_readfirstlane_b32 s26, v138
	v_add_u32_e32 v128, 0x4000, v140
	v_lshl_add_u64 v[136:137], v[136:137], 0, s[10:11]
	s_mov_b32 m0, s26
	v_readfirstlane_b32 s26, v128
	v_add_u32_e32 v128, 0x5000, v140
	global_load_lds_dwordx4 v[136:137], off
	v_lshl_add_u64 v[136:137], v[132:133], 0, 64
	s_mov_b32 m0, s26
	v_readfirstlane_b32 s26, v128
	global_load_lds_dwordx4 v[136:137], off
	v_lshl_add_u64 v[132:133], v[132:133], 0, s[6:7]
	s_mov_b32 m0, s26
	s_nop 0
	global_load_lds_dwordx4 v[132:133], off
	s_branch .LBB0_1499
